# experts sweep: 4 tokens sorted in one pass (shared lane masks, last 3 exchange levels skipped), final LayerNorm takes x from registers instead of reloading
# speedup vs baseline: 1.0727x; 1.0075x over previous
.Lex_half:
	s_lshl_b32 s10, s12, 2
	v_add_u32_e32 v64, s10, v79
	v_ashrrev_i32_e32 v65, 31, v64
	v_lshl_add_u64 v[64:65], s[28:29], 0, v[64:65]
	v_lshlrev_b64 v[0:1], 11, v[64:65]
	v_lshl_add_u64 v[0:1], v[80:81], 0, v[0:1]
	global_load_dwordx4 v[216:219], v[0:1], off
	global_load_dwordx4 v[220:223], v[0:1], off offset:16
	s_lshl_b32 s10, s12, 2
	s_add_i32 s10, s10, 1
	v_add_u32_e32 v64, s10, v79
	v_ashrrev_i32_e32 v65, 31, v64
	v_lshl_add_u64 v[64:65], s[28:29], 0, v[64:65]
	v_lshlrev_b64 v[0:1], 11, v[64:65]
	v_lshl_add_u64 v[0:1], v[80:81], 0, v[0:1]
	global_load_dwordx4 v[224:227], v[0:1], off
	global_load_dwordx4 v[228:231], v[0:1], off offset:16
	s_lshl_b32 s10, s12, 2
	s_add_i32 s10, s10, 2
	v_add_u32_e32 v64, s10, v79
	v_ashrrev_i32_e32 v65, 31, v64
	v_lshl_add_u64 v[64:65], s[28:29], 0, v[64:65]
	v_lshlrev_b64 v[0:1], 11, v[64:65]
	v_lshl_add_u64 v[0:1], v[80:81], 0, v[0:1]
	global_load_dwordx4 v[232:235], v[0:1], off
	global_load_dwordx4 v[236:239], v[0:1], off offset:16
	s_lshl_b32 s10, s12, 2
	s_add_i32 s10, s10, 3
	v_add_u32_e32 v64, s10, v79
	v_ashrrev_i32_e32 v65, 31, v64
	v_lshl_add_u64 v[64:65], s[28:29], 0, v[64:65]
	v_lshlrev_b64 v[0:1], 11, v[64:65]
	v_lshl_add_u64 v[0:1], v[80:81], 0, v[0:1]
	global_load_dwordx4 v[240:243], v[0:1], off
	global_load_dwordx4 v[244:247], v[0:1], off offset:16
	s_lshl_b32 s10, s12, 2
	v_add_u32_e32 v255, s10, v79
	v_lshlrev_b32_e32 v255, 11, v255
	v_and_b32_e32 v20, 63, v214
	v_lshl_add_u32 v22, v20, 4, v255
	ds_read_b32 v4, v22 offset:0
	ds_read_b32 v5, v22 offset:1024
	ds_read_b32 v6, v22 offset:2048
	ds_read_b32 v7, v22 offset:3072
	ds_read_b32 v8, v22 offset:4096
	ds_read_b32 v9, v22 offset:5120
	ds_read_b32 v10, v22 offset:6144
	ds_read_b32 v11, v22 offset:7168
	v_or_b32_e32 v23, 64, v20
	s_waitcnt lgkmcnt(0)
	v_lshl_or_b32 v4, v4, 7, v20
	v_lshl_or_b32 v5, v5, 7, v23
	v_lshl_or_b32 v6, v6, 7, v20
	v_lshl_or_b32 v7, v7, 7, v23
	v_lshl_or_b32 v8, v8, 7, v20
	v_lshl_or_b32 v9, v9, 7, v23
	v_lshl_or_b32 v10, v10, 7, v20
	v_lshl_or_b32 v11, v11, 7, v23
	v_xor_b32_e32 v21, 1, v20
	v_lshlrev_b32_e32 v21, 2, v21
	ds_bpermute_b32 v12, v21, v4
	ds_bpermute_b32 v13, v21, v5
	ds_bpermute_b32 v14, v21, v6
	ds_bpermute_b32 v15, v21, v7
	ds_bpermute_b32 v16, v21, v8
	ds_bpermute_b32 v17, v21, v9
	ds_bpermute_b32 v18, v21, v10
	ds_bpermute_b32 v19, v21, v11
	v_bfe_u32 v22, v20, 0, 1
	v_bfe_u32 v23, v20, 1, 1
	v_xor_b32_e32 v22, v22, v23
	v_cmp_eq_u32_e32 vcc, 0, v22
	s_waitcnt lgkmcnt(6)
	v_min_u32_e32 v22, v4, v12
	v_max_u32_e32 v23, v4, v12
	v_min_u32_e32 v24, v5, v13
	v_max_u32_e32 v25, v5, v13
	v_cndmask_b32_e32 v4, v23, v22, vcc
	v_cndmask_b32_e32 v5, v25, v24, vcc
	s_waitcnt lgkmcnt(4)
	v_min_u32_e32 v22, v6, v14
	v_max_u32_e32 v23, v6, v14
	v_min_u32_e32 v24, v7, v15
	v_max_u32_e32 v25, v7, v15
	v_cndmask_b32_e32 v6, v23, v22, vcc
	v_cndmask_b32_e32 v7, v25, v24, vcc
	s_waitcnt lgkmcnt(2)
	v_min_u32_e32 v22, v8, v16
	v_max_u32_e32 v23, v8, v16
	v_min_u32_e32 v24, v9, v17
	v_max_u32_e32 v25, v9, v17
	v_cndmask_b32_e32 v8, v23, v22, vcc
	v_cndmask_b32_e32 v9, v25, v24, vcc
	s_waitcnt lgkmcnt(0)
	v_min_u32_e32 v22, v10, v18
	v_max_u32_e32 v23, v10, v18
	v_min_u32_e32 v24, v11, v19
	v_max_u32_e32 v25, v11, v19
	v_cndmask_b32_e32 v10, v23, v22, vcc
	v_cndmask_b32_e32 v11, v25, v24, vcc
	v_xor_b32_e32 v21, 2, v20
	v_lshlrev_b32_e32 v21, 2, v21
	ds_bpermute_b32 v12, v21, v4
	ds_bpermute_b32 v13, v21, v5
	ds_bpermute_b32 v14, v21, v6
	ds_bpermute_b32 v15, v21, v7
	ds_bpermute_b32 v16, v21, v8
	ds_bpermute_b32 v17, v21, v9
	ds_bpermute_b32 v18, v21, v10
	ds_bpermute_b32 v19, v21, v11
	v_bfe_u32 v22, v20, 1, 1
	v_bfe_u32 v23, v20, 2, 1
	v_xor_b32_e32 v22, v22, v23
	v_cmp_eq_u32_e32 vcc, 0, v22
	s_waitcnt lgkmcnt(6)
	v_min_u32_e32 v22, v4, v12
	v_max_u32_e32 v23, v4, v12
	v_min_u32_e32 v24, v5, v13
	v_max_u32_e32 v25, v5, v13
	v_cndmask_b32_e32 v4, v23, v22, vcc
	v_cndmask_b32_e32 v5, v25, v24, vcc
	s_waitcnt lgkmcnt(4)
	v_min_u32_e32 v22, v6, v14
	v_max_u32_e32 v23, v6, v14
	v_min_u32_e32 v24, v7, v15
	v_max_u32_e32 v25, v7, v15
	v_cndmask_b32_e32 v6, v23, v22, vcc
	v_cndmask_b32_e32 v7, v25, v24, vcc
	s_waitcnt lgkmcnt(2)
	v_min_u32_e32 v22, v8, v16
	v_max_u32_e32 v23, v8, v16
	v_min_u32_e32 v24, v9, v17
	v_max_u32_e32 v25, v9, v17
	v_cndmask_b32_e32 v8, v23, v22, vcc
	v_cndmask_b32_e32 v9, v25, v24, vcc
	s_waitcnt lgkmcnt(0)
	v_min_u32_e32 v22, v10, v18
	v_max_u32_e32 v23, v10, v18
	v_min_u32_e32 v24, v11, v19
	v_max_u32_e32 v25, v11, v19
	v_cndmask_b32_e32 v10, v23, v22, vcc
	v_cndmask_b32_e32 v11, v25, v24, vcc
	v_xor_b32_e32 v21, 1, v20
	v_lshlrev_b32_e32 v21, 2, v21
	ds_bpermute_b32 v12, v21, v4
	ds_bpermute_b32 v13, v21, v5
	ds_bpermute_b32 v14, v21, v6
	ds_bpermute_b32 v15, v21, v7
	ds_bpermute_b32 v16, v21, v8
	ds_bpermute_b32 v17, v21, v9
	ds_bpermute_b32 v18, v21, v10
	ds_bpermute_b32 v19, v21, v11
	v_bfe_u32 v22, v20, 0, 1
	v_bfe_u32 v23, v20, 2, 1
	v_xor_b32_e32 v22, v22, v23
	v_cmp_eq_u32_e32 vcc, 0, v22
	s_waitcnt lgkmcnt(6)
	v_min_u32_e32 v22, v4, v12
	v_max_u32_e32 v23, v4, v12
	v_min_u32_e32 v24, v5, v13
	v_max_u32_e32 v25, v5, v13
	v_cndmask_b32_e32 v4, v23, v22, vcc
	v_cndmask_b32_e32 v5, v25, v24, vcc
	s_waitcnt lgkmcnt(4)
	v_min_u32_e32 v22, v6, v14
	v_max_u32_e32 v23, v6, v14
	v_min_u32_e32 v24, v7, v15
	v_max_u32_e32 v25, v7, v15
	v_cndmask_b32_e32 v6, v23, v22, vcc
	v_cndmask_b32_e32 v7, v25, v24, vcc
	s_waitcnt lgkmcnt(2)
	v_min_u32_e32 v22, v8, v16
	v_max_u32_e32 v23, v8, v16
	v_min_u32_e32 v24, v9, v17
	v_max_u32_e32 v25, v9, v17
	v_cndmask_b32_e32 v8, v23, v22, vcc
	v_cndmask_b32_e32 v9, v25, v24, vcc
	s_waitcnt lgkmcnt(0)
	v_min_u32_e32 v22, v10, v18
	v_max_u32_e32 v23, v10, v18
	v_min_u32_e32 v24, v11, v19
	v_max_u32_e32 v25, v11, v19
	v_cndmask_b32_e32 v10, v23, v22, vcc
	v_cndmask_b32_e32 v11, v25, v24, vcc
	v_xor_b32_e32 v21, 4, v20
	v_lshlrev_b32_e32 v21, 2, v21
	ds_bpermute_b32 v12, v21, v4
	ds_bpermute_b32 v13, v21, v5
	ds_bpermute_b32 v14, v21, v6
	ds_bpermute_b32 v15, v21, v7
	ds_bpermute_b32 v16, v21, v8
	ds_bpermute_b32 v17, v21, v9
	ds_bpermute_b32 v18, v21, v10
	ds_bpermute_b32 v19, v21, v11
	v_bfe_u32 v22, v20, 2, 1
	v_bfe_u32 v23, v20, 3, 1
	v_xor_b32_e32 v22, v22, v23
	v_cmp_eq_u32_e32 vcc, 0, v22
	s_waitcnt lgkmcnt(6)
	v_min_u32_e32 v22, v4, v12
	v_max_u32_e32 v23, v4, v12
	v_min_u32_e32 v24, v5, v13
	v_max_u32_e32 v25, v5, v13
	v_cndmask_b32_e32 v4, v23, v22, vcc
	v_cndmask_b32_e32 v5, v25, v24, vcc
	s_waitcnt lgkmcnt(4)
	v_min_u32_e32 v22, v6, v14
	v_max_u32_e32 v23, v6, v14
	v_min_u32_e32 v24, v7, v15
	v_max_u32_e32 v25, v7, v15
	v_cndmask_b32_e32 v6, v23, v22, vcc
	v_cndmask_b32_e32 v7, v25, v24, vcc
	s_waitcnt lgkmcnt(2)
	v_min_u32_e32 v22, v8, v16
	v_max_u32_e32 v23, v8, v16
	v_min_u32_e32 v24, v9, v17
	v_max_u32_e32 v25, v9, v17
	v_cndmask_b32_e32 v8, v23, v22, vcc
	v_cndmask_b32_e32 v9, v25, v24, vcc
	s_waitcnt lgkmcnt(0)
	v_min_u32_e32 v22, v10, v18
	v_max_u32_e32 v23, v10, v18
	v_min_u32_e32 v24, v11, v19
	v_max_u32_e32 v25, v11, v19
	v_cndmask_b32_e32 v10, v23, v22, vcc
	v_cndmask_b32_e32 v11, v25, v24, vcc
	v_xor_b32_e32 v21, 2, v20
	v_lshlrev_b32_e32 v21, 2, v21
	ds_bpermute_b32 v12, v21, v4
	ds_bpermute_b32 v13, v21, v5
	ds_bpermute_b32 v14, v21, v6
	ds_bpermute_b32 v15, v21, v7
	ds_bpermute_b32 v16, v21, v8
	ds_bpermute_b32 v17, v21, v9
	ds_bpermute_b32 v18, v21, v10
	ds_bpermute_b32 v19, v21, v11
	v_bfe_u32 v22, v20, 1, 1
	v_bfe_u32 v23, v20, 3, 1
	v_xor_b32_e32 v22, v22, v23
	v_cmp_eq_u32_e32 vcc, 0, v22
	s_waitcnt lgkmcnt(6)
	v_min_u32_e32 v22, v4, v12
	v_max_u32_e32 v23, v4, v12
	v_min_u32_e32 v24, v5, v13
	v_max_u32_e32 v25, v5, v13
	v_cndmask_b32_e32 v4, v23, v22, vcc
	v_cndmask_b32_e32 v5, v25, v24, vcc
	s_waitcnt lgkmcnt(4)
	v_min_u32_e32 v22, v6, v14
	v_max_u32_e32 v23, v6, v14
	v_min_u32_e32 v24, v7, v15
	v_max_u32_e32 v25, v7, v15
	v_cndmask_b32_e32 v6, v23, v22, vcc
	v_cndmask_b32_e32 v7, v25, v24, vcc
	s_waitcnt lgkmcnt(2)
	v_min_u32_e32 v22, v8, v16
	v_max_u32_e32 v23, v8, v16
	v_min_u32_e32 v24, v9, v17
	v_max_u32_e32 v25, v9, v17
	v_cndmask_b32_e32 v8, v23, v22, vcc
	v_cndmask_b32_e32 v9, v25, v24, vcc
	s_waitcnt lgkmcnt(0)
	v_min_u32_e32 v22, v10, v18
	v_max_u32_e32 v23, v10, v18
	v_min_u32_e32 v24, v11, v19
	v_max_u32_e32 v25, v11, v19
	v_cndmask_b32_e32 v10, v23, v22, vcc
	v_cndmask_b32_e32 v11, v25, v24, vcc
	v_xor_b32_e32 v21, 1, v20
	v_lshlrev_b32_e32 v21, 2, v21
	ds_bpermute_b32 v12, v21, v4
	ds_bpermute_b32 v13, v21, v5
	ds_bpermute_b32 v14, v21, v6
	ds_bpermute_b32 v15, v21, v7
	ds_bpermute_b32 v16, v21, v8
	ds_bpermute_b32 v17, v21, v9
	ds_bpermute_b32 v18, v21, v10
	ds_bpermute_b32 v19, v21, v11
	v_bfe_u32 v22, v20, 0, 1
	v_bfe_u32 v23, v20, 3, 1
	v_xor_b32_e32 v22, v22, v23
	v_cmp_eq_u32_e32 vcc, 0, v22
	s_waitcnt lgkmcnt(6)
	v_min_u32_e32 v22, v4, v12
	v_max_u32_e32 v23, v4, v12
	v_min_u32_e32 v24, v5, v13
	v_max_u32_e32 v25, v5, v13
	v_cndmask_b32_e32 v4, v23, v22, vcc
	v_cndmask_b32_e32 v5, v25, v24, vcc
	s_waitcnt lgkmcnt(4)
	v_min_u32_e32 v22, v6, v14
	v_max_u32_e32 v23, v6, v14
	v_min_u32_e32 v24, v7, v15
	v_max_u32_e32 v25, v7, v15
	v_cndmask_b32_e32 v6, v23, v22, vcc
	v_cndmask_b32_e32 v7, v25, v24, vcc
	s_waitcnt lgkmcnt(2)
	v_min_u32_e32 v22, v8, v16
	v_max_u32_e32 v23, v8, v16
	v_min_u32_e32 v24, v9, v17
	v_max_u32_e32 v25, v9, v17
	v_cndmask_b32_e32 v8, v23, v22, vcc
	v_cndmask_b32_e32 v9, v25, v24, vcc
	s_waitcnt lgkmcnt(0)
	v_min_u32_e32 v22, v10, v18
	v_max_u32_e32 v23, v10, v18
	v_min_u32_e32 v24, v11, v19
	v_max_u32_e32 v25, v11, v19
	v_cndmask_b32_e32 v10, v23, v22, vcc
	v_cndmask_b32_e32 v11, v25, v24, vcc
	v_xor_b32_e32 v21, 8, v20
	v_lshlrev_b32_e32 v21, 2, v21
	ds_bpermute_b32 v12, v21, v4
	ds_bpermute_b32 v13, v21, v5
	ds_bpermute_b32 v14, v21, v6
	ds_bpermute_b32 v15, v21, v7
	ds_bpermute_b32 v16, v21, v8
	ds_bpermute_b32 v17, v21, v9
	ds_bpermute_b32 v18, v21, v10
	ds_bpermute_b32 v19, v21, v11
	v_bfe_u32 v22, v20, 3, 1
	v_bfe_u32 v23, v20, 4, 1
	v_xor_b32_e32 v22, v22, v23
	v_cmp_eq_u32_e32 vcc, 0, v22
	s_waitcnt lgkmcnt(6)
	v_min_u32_e32 v22, v4, v12
	v_max_u32_e32 v23, v4, v12
	v_min_u32_e32 v24, v5, v13
	v_max_u32_e32 v25, v5, v13
	v_cndmask_b32_e32 v4, v23, v22, vcc
	v_cndmask_b32_e32 v5, v25, v24, vcc
	s_waitcnt lgkmcnt(4)
	v_min_u32_e32 v22, v6, v14
	v_max_u32_e32 v23, v6, v14
	v_min_u32_e32 v24, v7, v15
	v_max_u32_e32 v25, v7, v15
	v_cndmask_b32_e32 v6, v23, v22, vcc
	v_cndmask_b32_e32 v7, v25, v24, vcc
	s_waitcnt lgkmcnt(2)
	v_min_u32_e32 v22, v8, v16
	v_max_u32_e32 v23, v8, v16
	v_min_u32_e32 v24, v9, v17
	v_max_u32_e32 v25, v9, v17
	v_cndmask_b32_e32 v8, v23, v22, vcc
	v_cndmask_b32_e32 v9, v25, v24, vcc
	s_waitcnt lgkmcnt(0)
	v_min_u32_e32 v22, v10, v18
	v_max_u32_e32 v23, v10, v18
	v_min_u32_e32 v24, v11, v19
	v_max_u32_e32 v25, v11, v19
	v_cndmask_b32_e32 v10, v23, v22, vcc
	v_cndmask_b32_e32 v11, v25, v24, vcc
	v_xor_b32_e32 v21, 4, v20
	v_lshlrev_b32_e32 v21, 2, v21
	ds_bpermute_b32 v12, v21, v4
	ds_bpermute_b32 v13, v21, v5
	ds_bpermute_b32 v14, v21, v6
	ds_bpermute_b32 v15, v21, v7
	ds_bpermute_b32 v16, v21, v8
	ds_bpermute_b32 v17, v21, v9
	ds_bpermute_b32 v18, v21, v10
	ds_bpermute_b32 v19, v21, v11
	v_bfe_u32 v22, v20, 2, 1
	v_bfe_u32 v23, v20, 4, 1
	v_xor_b32_e32 v22, v22, v23
	v_cmp_eq_u32_e32 vcc, 0, v22
	s_waitcnt lgkmcnt(6)
	v_min_u32_e32 v22, v4, v12
	v_max_u32_e32 v23, v4, v12
	v_min_u32_e32 v24, v5, v13
	v_max_u32_e32 v25, v5, v13
	v_cndmask_b32_e32 v4, v23, v22, vcc
	v_cndmask_b32_e32 v5, v25, v24, vcc
	s_waitcnt lgkmcnt(4)
	v_min_u32_e32 v22, v6, v14
	v_max_u32_e32 v23, v6, v14
	v_min_u32_e32 v24, v7, v15
	v_max_u32_e32 v25, v7, v15
	v_cndmask_b32_e32 v6, v23, v22, vcc
	v_cndmask_b32_e32 v7, v25, v24, vcc
	s_waitcnt lgkmcnt(2)
	v_min_u32_e32 v22, v8, v16
	v_max_u32_e32 v23, v8, v16
	v_min_u32_e32 v24, v9, v17
	v_max_u32_e32 v25, v9, v17
	v_cndmask_b32_e32 v8, v23, v22, vcc
	v_cndmask_b32_e32 v9, v25, v24, vcc
	s_waitcnt lgkmcnt(0)
	v_min_u32_e32 v22, v10, v18
	v_max_u32_e32 v23, v10, v18
	v_min_u32_e32 v24, v11, v19
	v_max_u32_e32 v25, v11, v19
	v_cndmask_b32_e32 v10, v23, v22, vcc
	v_cndmask_b32_e32 v11, v25, v24, vcc
	v_xor_b32_e32 v21, 2, v20
	v_lshlrev_b32_e32 v21, 2, v21
	ds_bpermute_b32 v12, v21, v4
	ds_bpermute_b32 v13, v21, v5
	ds_bpermute_b32 v14, v21, v6
	ds_bpermute_b32 v15, v21, v7
	ds_bpermute_b32 v16, v21, v8
	ds_bpermute_b32 v17, v21, v9
	ds_bpermute_b32 v18, v21, v10
	ds_bpermute_b32 v19, v21, v11
	v_bfe_u32 v22, v20, 1, 1
	v_bfe_u32 v23, v20, 4, 1
	v_xor_b32_e32 v22, v22, v23
	v_cmp_eq_u32_e32 vcc, 0, v22
	s_waitcnt lgkmcnt(6)
	v_min_u32_e32 v22, v4, v12
	v_max_u32_e32 v23, v4, v12
	v_min_u32_e32 v24, v5, v13
	v_max_u32_e32 v25, v5, v13
	v_cndmask_b32_e32 v4, v23, v22, vcc
	v_cndmask_b32_e32 v5, v25, v24, vcc
	s_waitcnt lgkmcnt(4)
	v_min_u32_e32 v22, v6, v14
	v_max_u32_e32 v23, v6, v14
	v_min_u32_e32 v24, v7, v15
	v_max_u32_e32 v25, v7, v15
	v_cndmask_b32_e32 v6, v23, v22, vcc
	v_cndmask_b32_e32 v7, v25, v24, vcc
	s_waitcnt lgkmcnt(2)
	v_min_u32_e32 v22, v8, v16
	v_max_u32_e32 v23, v8, v16
	v_min_u32_e32 v24, v9, v17
	v_max_u32_e32 v25, v9, v17
	v_cndmask_b32_e32 v8, v23, v22, vcc
	v_cndmask_b32_e32 v9, v25, v24, vcc
	s_waitcnt lgkmcnt(0)
	v_min_u32_e32 v22, v10, v18
	v_max_u32_e32 v23, v10, v18
	v_min_u32_e32 v24, v11, v19
	v_max_u32_e32 v25, v11, v19
	v_cndmask_b32_e32 v10, v23, v22, vcc
	v_cndmask_b32_e32 v11, v25, v24, vcc
	v_xor_b32_e32 v21, 1, v20
	v_lshlrev_b32_e32 v21, 2, v21
	ds_bpermute_b32 v12, v21, v4
	ds_bpermute_b32 v13, v21, v5
	ds_bpermute_b32 v14, v21, v6
	ds_bpermute_b32 v15, v21, v7
	ds_bpermute_b32 v16, v21, v8
	ds_bpermute_b32 v17, v21, v9
	ds_bpermute_b32 v18, v21, v10
	ds_bpermute_b32 v19, v21, v11
	v_bfe_u32 v22, v20, 0, 1
	v_bfe_u32 v23, v20, 4, 1
	v_xor_b32_e32 v22, v22, v23
	v_cmp_eq_u32_e32 vcc, 0, v22
	s_waitcnt lgkmcnt(6)
	v_min_u32_e32 v22, v4, v12
	v_max_u32_e32 v23, v4, v12
	v_min_u32_e32 v24, v5, v13
	v_max_u32_e32 v25, v5, v13
	v_cndmask_b32_e32 v4, v23, v22, vcc
	v_cndmask_b32_e32 v5, v25, v24, vcc
	s_waitcnt lgkmcnt(4)
	v_min_u32_e32 v22, v6, v14
	v_max_u32_e32 v23, v6, v14
	v_min_u32_e32 v24, v7, v15
	v_max_u32_e32 v25, v7, v15
	v_cndmask_b32_e32 v6, v23, v22, vcc
	v_cndmask_b32_e32 v7, v25, v24, vcc
	s_waitcnt lgkmcnt(2)
	v_min_u32_e32 v22, v8, v16
	v_max_u32_e32 v23, v8, v16
	v_min_u32_e32 v24, v9, v17
	v_max_u32_e32 v25, v9, v17
	v_cndmask_b32_e32 v8, v23, v22, vcc
	v_cndmask_b32_e32 v9, v25, v24, vcc
	s_waitcnt lgkmcnt(0)
	v_min_u32_e32 v22, v10, v18
	v_max_u32_e32 v23, v10, v18
	v_min_u32_e32 v24, v11, v19
	v_max_u32_e32 v25, v11, v19
	v_cndmask_b32_e32 v10, v23, v22, vcc
	v_cndmask_b32_e32 v11, v25, v24, vcc
	v_xor_b32_e32 v21, 16, v20
	v_lshlrev_b32_e32 v21, 2, v21
	ds_bpermute_b32 v12, v21, v4
	ds_bpermute_b32 v13, v21, v5
	ds_bpermute_b32 v14, v21, v6
	ds_bpermute_b32 v15, v21, v7
	ds_bpermute_b32 v16, v21, v8
	ds_bpermute_b32 v17, v21, v9
	ds_bpermute_b32 v18, v21, v10
	ds_bpermute_b32 v19, v21, v11
	v_bfe_u32 v22, v20, 4, 1
	v_bfe_u32 v23, v20, 5, 1
	v_xor_b32_e32 v22, v22, v23
	v_cmp_eq_u32_e32 vcc, 0, v22
	s_waitcnt lgkmcnt(6)
	v_min_u32_e32 v22, v4, v12
	v_max_u32_e32 v23, v4, v12
	v_min_u32_e32 v24, v5, v13
	v_max_u32_e32 v25, v5, v13
	v_cndmask_b32_e32 v4, v23, v22, vcc
	v_cndmask_b32_e32 v5, v25, v24, vcc
	s_waitcnt lgkmcnt(4)
	v_min_u32_e32 v22, v6, v14
	v_max_u32_e32 v23, v6, v14
	v_min_u32_e32 v24, v7, v15
	v_max_u32_e32 v25, v7, v15
	v_cndmask_b32_e32 v6, v23, v22, vcc
	v_cndmask_b32_e32 v7, v25, v24, vcc
	s_waitcnt lgkmcnt(2)
	v_min_u32_e32 v22, v8, v16
	v_max_u32_e32 v23, v8, v16
	v_min_u32_e32 v24, v9, v17
	v_max_u32_e32 v25, v9, v17
	v_cndmask_b32_e32 v8, v23, v22, vcc
	v_cndmask_b32_e32 v9, v25, v24, vcc
	s_waitcnt lgkmcnt(0)
	v_min_u32_e32 v22, v10, v18
	v_max_u32_e32 v23, v10, v18
	v_min_u32_e32 v24, v11, v19
	v_max_u32_e32 v25, v11, v19
	v_cndmask_b32_e32 v10, v23, v22, vcc
	v_cndmask_b32_e32 v11, v25, v24, vcc
	v_xor_b32_e32 v21, 8, v20
	v_lshlrev_b32_e32 v21, 2, v21
	ds_bpermute_b32 v12, v21, v4
	ds_bpermute_b32 v13, v21, v5
	ds_bpermute_b32 v14, v21, v6
	ds_bpermute_b32 v15, v21, v7
	ds_bpermute_b32 v16, v21, v8
	ds_bpermute_b32 v17, v21, v9
	ds_bpermute_b32 v18, v21, v10
	ds_bpermute_b32 v19, v21, v11
	v_bfe_u32 v22, v20, 3, 1
	v_bfe_u32 v23, v20, 5, 1
	v_xor_b32_e32 v22, v22, v23
	v_cmp_eq_u32_e32 vcc, 0, v22
	s_waitcnt lgkmcnt(6)
	v_min_u32_e32 v22, v4, v12
	v_max_u32_e32 v23, v4, v12
	v_min_u32_e32 v24, v5, v13
	v_max_u32_e32 v25, v5, v13
	v_cndmask_b32_e32 v4, v23, v22, vcc
	v_cndmask_b32_e32 v5, v25, v24, vcc
	s_waitcnt lgkmcnt(4)
	v_min_u32_e32 v22, v6, v14
	v_max_u32_e32 v23, v6, v14
	v_min_u32_e32 v24, v7, v15
	v_max_u32_e32 v25, v7, v15
	v_cndmask_b32_e32 v6, v23, v22, vcc
	v_cndmask_b32_e32 v7, v25, v24, vcc
	s_waitcnt lgkmcnt(2)
	v_min_u32_e32 v22, v8, v16
	v_max_u32_e32 v23, v8, v16
	v_min_u32_e32 v24, v9, v17
	v_max_u32_e32 v25, v9, v17
	v_cndmask_b32_e32 v8, v23, v22, vcc
	v_cndmask_b32_e32 v9, v25, v24, vcc
	s_waitcnt lgkmcnt(0)
	v_min_u32_e32 v22, v10, v18
	v_max_u32_e32 v23, v10, v18
	v_min_u32_e32 v24, v11, v19
	v_max_u32_e32 v25, v11, v19
	v_cndmask_b32_e32 v10, v23, v22, vcc
	v_cndmask_b32_e32 v11, v25, v24, vcc
	v_xor_b32_e32 v21, 4, v20
	v_lshlrev_b32_e32 v21, 2, v21
	ds_bpermute_b32 v12, v21, v4
	ds_bpermute_b32 v13, v21, v5
	ds_bpermute_b32 v14, v21, v6
	ds_bpermute_b32 v15, v21, v7
	ds_bpermute_b32 v16, v21, v8
	ds_bpermute_b32 v17, v21, v9
	ds_bpermute_b32 v18, v21, v10
	ds_bpermute_b32 v19, v21, v11
	v_bfe_u32 v22, v20, 2, 1
	v_bfe_u32 v23, v20, 5, 1
	v_xor_b32_e32 v22, v22, v23
	v_cmp_eq_u32_e32 vcc, 0, v22
	s_waitcnt lgkmcnt(6)
	v_min_u32_e32 v22, v4, v12
	v_max_u32_e32 v23, v4, v12
	v_min_u32_e32 v24, v5, v13
	v_max_u32_e32 v25, v5, v13
	v_cndmask_b32_e32 v4, v23, v22, vcc
	v_cndmask_b32_e32 v5, v25, v24, vcc
	s_waitcnt lgkmcnt(4)
	v_min_u32_e32 v22, v6, v14
	v_max_u32_e32 v23, v6, v14
	v_min_u32_e32 v24, v7, v15
	v_max_u32_e32 v25, v7, v15
	v_cndmask_b32_e32 v6, v23, v22, vcc
	v_cndmask_b32_e32 v7, v25, v24, vcc
	s_waitcnt lgkmcnt(2)
	v_min_u32_e32 v22, v8, v16
	v_max_u32_e32 v23, v8, v16
	v_min_u32_e32 v24, v9, v17
	v_max_u32_e32 v25, v9, v17
	v_cndmask_b32_e32 v8, v23, v22, vcc
	v_cndmask_b32_e32 v9, v25, v24, vcc
	s_waitcnt lgkmcnt(0)
	v_min_u32_e32 v22, v10, v18
	v_max_u32_e32 v23, v10, v18
	v_min_u32_e32 v24, v11, v19
	v_max_u32_e32 v25, v11, v19
	v_cndmask_b32_e32 v10, v23, v22, vcc
	v_cndmask_b32_e32 v11, v25, v24, vcc
	v_xor_b32_e32 v21, 2, v20
	v_lshlrev_b32_e32 v21, 2, v21
	ds_bpermute_b32 v12, v21, v4
	ds_bpermute_b32 v13, v21, v5
	ds_bpermute_b32 v14, v21, v6
	ds_bpermute_b32 v15, v21, v7
	ds_bpermute_b32 v16, v21, v8
	ds_bpermute_b32 v17, v21, v9
	ds_bpermute_b32 v18, v21, v10
	ds_bpermute_b32 v19, v21, v11
	v_bfe_u32 v22, v20, 1, 1
	v_bfe_u32 v23, v20, 5, 1
	v_xor_b32_e32 v22, v22, v23
	v_cmp_eq_u32_e32 vcc, 0, v22
	s_waitcnt lgkmcnt(6)
	v_min_u32_e32 v22, v4, v12
	v_max_u32_e32 v23, v4, v12
	v_min_u32_e32 v24, v5, v13
	v_max_u32_e32 v25, v5, v13
	v_cndmask_b32_e32 v4, v23, v22, vcc
	v_cndmask_b32_e32 v5, v25, v24, vcc
	s_waitcnt lgkmcnt(4)
	v_min_u32_e32 v22, v6, v14
	v_max_u32_e32 v23, v6, v14
	v_min_u32_e32 v24, v7, v15
	v_max_u32_e32 v25, v7, v15
	v_cndmask_b32_e32 v6, v23, v22, vcc
	v_cndmask_b32_e32 v7, v25, v24, vcc
	s_waitcnt lgkmcnt(2)
	v_min_u32_e32 v22, v8, v16
	v_max_u32_e32 v23, v8, v16
	v_min_u32_e32 v24, v9, v17
	v_max_u32_e32 v25, v9, v17
	v_cndmask_b32_e32 v8, v23, v22, vcc
	v_cndmask_b32_e32 v9, v25, v24, vcc
	s_waitcnt lgkmcnt(0)
	v_min_u32_e32 v22, v10, v18
	v_max_u32_e32 v23, v10, v18
	v_min_u32_e32 v24, v11, v19
	v_max_u32_e32 v25, v11, v19
	v_cndmask_b32_e32 v10, v23, v22, vcc
	v_cndmask_b32_e32 v11, v25, v24, vcc
	v_xor_b32_e32 v21, 1, v20
	v_lshlrev_b32_e32 v21, 2, v21
	ds_bpermute_b32 v12, v21, v4
	ds_bpermute_b32 v13, v21, v5
	ds_bpermute_b32 v14, v21, v6
	ds_bpermute_b32 v15, v21, v7
	ds_bpermute_b32 v16, v21, v8
	ds_bpermute_b32 v17, v21, v9
	ds_bpermute_b32 v18, v21, v10
	ds_bpermute_b32 v19, v21, v11
	v_bfe_u32 v22, v20, 0, 1
	v_bfe_u32 v23, v20, 5, 1
	v_xor_b32_e32 v22, v22, v23
	v_cmp_eq_u32_e32 vcc, 0, v22
	s_waitcnt lgkmcnt(6)
	v_min_u32_e32 v22, v4, v12
	v_max_u32_e32 v23, v4, v12
	v_min_u32_e32 v24, v5, v13
	v_max_u32_e32 v25, v5, v13
	v_cndmask_b32_e32 v4, v23, v22, vcc
	v_cndmask_b32_e32 v5, v25, v24, vcc
	s_waitcnt lgkmcnt(4)
	v_min_u32_e32 v22, v6, v14
	v_max_u32_e32 v23, v6, v14
	v_min_u32_e32 v24, v7, v15
	v_max_u32_e32 v25, v7, v15
	v_cndmask_b32_e32 v6, v23, v22, vcc
	v_cndmask_b32_e32 v7, v25, v24, vcc
	s_waitcnt lgkmcnt(2)
	v_min_u32_e32 v22, v8, v16
	v_max_u32_e32 v23, v8, v16
	v_min_u32_e32 v24, v9, v17
	v_max_u32_e32 v25, v9, v17
	v_cndmask_b32_e32 v8, v23, v22, vcc
	v_cndmask_b32_e32 v9, v25, v24, vcc
	s_waitcnt lgkmcnt(0)
	v_min_u32_e32 v22, v10, v18
	v_max_u32_e32 v23, v10, v18
	v_min_u32_e32 v24, v11, v19
	v_max_u32_e32 v25, v11, v19
	v_cndmask_b32_e32 v10, v23, v22, vcc
	v_cndmask_b32_e32 v11, v25, v24, vcc
	v_xor_b32_e32 v21, 32, v20
	v_lshlrev_b32_e32 v21, 2, v21
	ds_bpermute_b32 v12, v21, v4
	ds_bpermute_b32 v13, v21, v5
	ds_bpermute_b32 v14, v21, v6
	ds_bpermute_b32 v15, v21, v7
	ds_bpermute_b32 v16, v21, v8
	ds_bpermute_b32 v17, v21, v9
	ds_bpermute_b32 v18, v21, v10
	ds_bpermute_b32 v19, v21, v11
	v_bfe_u32 v22, v20, 5, 1
	v_cmp_eq_u32_e32 vcc, 0, v22
	s_waitcnt lgkmcnt(6)
	v_min_u32_e32 v22, v4, v12
	v_max_u32_e32 v23, v4, v12
	v_min_u32_e32 v24, v5, v13
	v_max_u32_e32 v25, v5, v13
	v_cndmask_b32_e32 v4, v23, v22, vcc
	v_cndmask_b32_e32 v5, v24, v25, vcc
	s_waitcnt lgkmcnt(4)
	v_min_u32_e32 v22, v6, v14
	v_max_u32_e32 v23, v6, v14
	v_min_u32_e32 v24, v7, v15
	v_max_u32_e32 v25, v7, v15
	v_cndmask_b32_e32 v6, v23, v22, vcc
	v_cndmask_b32_e32 v7, v24, v25, vcc
	s_waitcnt lgkmcnt(2)
	v_min_u32_e32 v22, v8, v16
	v_max_u32_e32 v23, v8, v16
	v_min_u32_e32 v24, v9, v17
	v_max_u32_e32 v25, v9, v17
	v_cndmask_b32_e32 v8, v23, v22, vcc
	v_cndmask_b32_e32 v9, v24, v25, vcc
	s_waitcnt lgkmcnt(0)
	v_min_u32_e32 v22, v10, v18
	v_max_u32_e32 v23, v10, v18
	v_min_u32_e32 v24, v11, v19
	v_max_u32_e32 v25, v11, v19
	v_cndmask_b32_e32 v10, v23, v22, vcc
	v_cndmask_b32_e32 v11, v24, v25, vcc
	v_xor_b32_e32 v21, 16, v20
	v_lshlrev_b32_e32 v21, 2, v21
	ds_bpermute_b32 v12, v21, v4
	ds_bpermute_b32 v13, v21, v5
	ds_bpermute_b32 v14, v21, v6
	ds_bpermute_b32 v15, v21, v7
	ds_bpermute_b32 v16, v21, v8
	ds_bpermute_b32 v17, v21, v9
	ds_bpermute_b32 v18, v21, v10
	ds_bpermute_b32 v19, v21, v11
	v_bfe_u32 v22, v20, 4, 1
	v_cmp_eq_u32_e32 vcc, 0, v22
	s_waitcnt lgkmcnt(6)
	v_min_u32_e32 v22, v4, v12
	v_max_u32_e32 v23, v4, v12
	v_min_u32_e32 v24, v5, v13
	v_max_u32_e32 v25, v5, v13
	v_cndmask_b32_e32 v4, v23, v22, vcc
	v_cndmask_b32_e32 v5, v24, v25, vcc
	s_waitcnt lgkmcnt(4)
	v_min_u32_e32 v22, v6, v14
	v_max_u32_e32 v23, v6, v14
	v_min_u32_e32 v24, v7, v15
	v_max_u32_e32 v25, v7, v15
	v_cndmask_b32_e32 v6, v23, v22, vcc
	v_cndmask_b32_e32 v7, v24, v25, vcc
	s_waitcnt lgkmcnt(2)
	v_min_u32_e32 v22, v8, v16
	v_max_u32_e32 v23, v8, v16
	v_min_u32_e32 v24, v9, v17
	v_max_u32_e32 v25, v9, v17
	v_cndmask_b32_e32 v8, v23, v22, vcc
	v_cndmask_b32_e32 v9, v24, v25, vcc
	s_waitcnt lgkmcnt(0)
	v_min_u32_e32 v22, v10, v18
	v_max_u32_e32 v23, v10, v18
	v_min_u32_e32 v24, v11, v19
	v_max_u32_e32 v25, v11, v19
	v_cndmask_b32_e32 v10, v23, v22, vcc
	v_cndmask_b32_e32 v11, v24, v25, vcc
	v_xor_b32_e32 v21, 8, v20
	v_lshlrev_b32_e32 v21, 2, v21
	ds_bpermute_b32 v12, v21, v4
	ds_bpermute_b32 v13, v21, v5
	ds_bpermute_b32 v14, v21, v6
	ds_bpermute_b32 v15, v21, v7
	ds_bpermute_b32 v16, v21, v8
	ds_bpermute_b32 v17, v21, v9
	ds_bpermute_b32 v18, v21, v10
	ds_bpermute_b32 v19, v21, v11
	v_bfe_u32 v22, v20, 3, 1
	v_cmp_eq_u32_e32 vcc, 0, v22
	s_waitcnt lgkmcnt(6)
	v_min_u32_e32 v22, v4, v12
	v_max_u32_e32 v23, v4, v12
	v_min_u32_e32 v24, v5, v13
	v_max_u32_e32 v25, v5, v13
	v_cndmask_b32_e32 v4, v23, v22, vcc
	v_cndmask_b32_e32 v5, v24, v25, vcc
	s_waitcnt lgkmcnt(4)
	v_min_u32_e32 v22, v6, v14
	v_max_u32_e32 v23, v6, v14
	v_min_u32_e32 v24, v7, v15
	v_max_u32_e32 v25, v7, v15
	v_cndmask_b32_e32 v6, v23, v22, vcc
	v_cndmask_b32_e32 v7, v24, v25, vcc
	s_waitcnt lgkmcnt(2)
	v_min_u32_e32 v22, v8, v16
	v_max_u32_e32 v23, v8, v16
	v_min_u32_e32 v24, v9, v17
	v_max_u32_e32 v25, v9, v17
	v_cndmask_b32_e32 v8, v23, v22, vcc
	v_cndmask_b32_e32 v9, v24, v25, vcc
	s_waitcnt lgkmcnt(0)
	v_min_u32_e32 v22, v10, v18
	v_max_u32_e32 v23, v10, v18
	v_min_u32_e32 v24, v11, v19
	v_max_u32_e32 v25, v11, v19
	v_cndmask_b32_e32 v10, v23, v22, vcc
	v_cndmask_b32_e32 v11, v24, v25, vcc
	v_xor_b32_e32 v21, 4, v20
	v_lshlrev_b32_e32 v21, 2, v21
	ds_bpermute_b32 v12, v21, v4
	ds_bpermute_b32 v13, v21, v5
	ds_bpermute_b32 v14, v21, v6
	ds_bpermute_b32 v15, v21, v7
	ds_bpermute_b32 v16, v21, v8
	ds_bpermute_b32 v17, v21, v9
	ds_bpermute_b32 v18, v21, v10
	ds_bpermute_b32 v19, v21, v11
	v_bfe_u32 v22, v20, 2, 1
	v_cmp_eq_u32_e32 vcc, 0, v22
	s_waitcnt lgkmcnt(6)
	v_min_u32_e32 v22, v4, v12
	v_max_u32_e32 v23, v4, v12
	v_min_u32_e32 v24, v5, v13
	v_max_u32_e32 v25, v5, v13
	v_cndmask_b32_e32 v4, v23, v22, vcc
	v_cndmask_b32_e32 v5, v24, v25, vcc
	s_waitcnt lgkmcnt(4)
	v_min_u32_e32 v22, v6, v14
	v_max_u32_e32 v23, v6, v14
	v_min_u32_e32 v24, v7, v15
	v_max_u32_e32 v25, v7, v15
	v_cndmask_b32_e32 v6, v23, v22, vcc
	v_cndmask_b32_e32 v7, v24, v25, vcc
	s_waitcnt lgkmcnt(2)
	v_min_u32_e32 v22, v8, v16
	v_max_u32_e32 v23, v8, v16
	v_min_u32_e32 v24, v9, v17
	v_max_u32_e32 v25, v9, v17
	v_cndmask_b32_e32 v8, v23, v22, vcc
	v_cndmask_b32_e32 v9, v24, v25, vcc
	s_waitcnt lgkmcnt(0)
	v_min_u32_e32 v22, v10, v18
	v_max_u32_e32 v23, v10, v18
	v_min_u32_e32 v24, v11, v19
	v_max_u32_e32 v25, v11, v19
	v_cndmask_b32_e32 v10, v23, v22, vcc
	v_cndmask_b32_e32 v11, v24, v25, vcc
	v_xor_b32_e32 v21, 2, v20
	v_lshlrev_b32_e32 v21, 2, v21
	ds_bpermute_b32 v12, v21, v4
	ds_bpermute_b32 v13, v21, v5
	ds_bpermute_b32 v14, v21, v6
	ds_bpermute_b32 v15, v21, v7
	ds_bpermute_b32 v16, v21, v8
	ds_bpermute_b32 v17, v21, v9
	ds_bpermute_b32 v18, v21, v10
	ds_bpermute_b32 v19, v21, v11
	v_bfe_u32 v22, v20, 1, 1
	v_cmp_eq_u32_e32 vcc, 0, v22
	s_waitcnt lgkmcnt(6)
	v_min_u32_e32 v22, v4, v12
	v_max_u32_e32 v23, v4, v12
	v_min_u32_e32 v24, v5, v13
	v_max_u32_e32 v25, v5, v13
	v_cndmask_b32_e32 v4, v23, v22, vcc
	v_cndmask_b32_e32 v5, v24, v25, vcc
	s_waitcnt lgkmcnt(4)
	v_min_u32_e32 v22, v6, v14
	v_max_u32_e32 v23, v6, v14
	v_min_u32_e32 v24, v7, v15
	v_max_u32_e32 v25, v7, v15
	v_cndmask_b32_e32 v6, v23, v22, vcc
	v_cndmask_b32_e32 v7, v24, v25, vcc
	s_waitcnt lgkmcnt(2)
	v_min_u32_e32 v22, v8, v16
	v_max_u32_e32 v23, v8, v16
	v_min_u32_e32 v24, v9, v17
	v_max_u32_e32 v25, v9, v17
	v_cndmask_b32_e32 v8, v23, v22, vcc
	v_cndmask_b32_e32 v9, v24, v25, vcc
	s_waitcnt lgkmcnt(0)
	v_min_u32_e32 v22, v10, v18
	v_max_u32_e32 v23, v10, v18
	v_min_u32_e32 v24, v11, v19
	v_max_u32_e32 v25, v11, v19
	v_cndmask_b32_e32 v10, v23, v22, vcc
	v_cndmask_b32_e32 v11, v24, v25, vcc
	v_xor_b32_e32 v21, 1, v20
	v_lshlrev_b32_e32 v21, 2, v21
	ds_bpermute_b32 v12, v21, v4
	ds_bpermute_b32 v13, v21, v5
	ds_bpermute_b32 v14, v21, v6
	ds_bpermute_b32 v15, v21, v7
	ds_bpermute_b32 v16, v21, v8
	ds_bpermute_b32 v17, v21, v9
	ds_bpermute_b32 v18, v21, v10
	ds_bpermute_b32 v19, v21, v11
	v_bfe_u32 v22, v20, 0, 1
	v_cmp_eq_u32_e32 vcc, 0, v22
	s_waitcnt lgkmcnt(6)
	v_min_u32_e32 v22, v4, v12
	v_max_u32_e32 v23, v4, v12
	v_min_u32_e32 v24, v5, v13
	v_max_u32_e32 v25, v5, v13
	v_cndmask_b32_e32 v4, v23, v22, vcc
	v_cndmask_b32_e32 v5, v24, v25, vcc
	s_waitcnt lgkmcnt(4)
	v_min_u32_e32 v22, v6, v14
	v_max_u32_e32 v23, v6, v14
	v_min_u32_e32 v24, v7, v15
	v_max_u32_e32 v25, v7, v15
	v_cndmask_b32_e32 v6, v23, v22, vcc
	v_cndmask_b32_e32 v7, v24, v25, vcc
	s_waitcnt lgkmcnt(2)
	v_min_u32_e32 v22, v8, v16
	v_max_u32_e32 v23, v8, v16
	v_min_u32_e32 v24, v9, v17
	v_max_u32_e32 v25, v9, v17
	v_cndmask_b32_e32 v8, v23, v22, vcc
	v_cndmask_b32_e32 v9, v24, v25, vcc
	s_waitcnt lgkmcnt(0)
	v_min_u32_e32 v22, v10, v18
	v_max_u32_e32 v23, v10, v18
	v_min_u32_e32 v24, v11, v19
	v_max_u32_e32 v25, v11, v19
	v_cndmask_b32_e32 v10, v23, v22, vcc
	v_cndmask_b32_e32 v11, v24, v25, vcc
	v_min_u32_e32 v22, v4, v5
	v_max_u32_e32 v5, v4, v5
	v_mov_b32_e32 v4, v22
	v_min_u32_e32 v22, v6, v7
	v_max_u32_e32 v7, v6, v7
	v_mov_b32_e32 v6, v22
	v_min_u32_e32 v22, v8, v9
	v_max_u32_e32 v9, v8, v9
	v_mov_b32_e32 v8, v22
	v_min_u32_e32 v22, v10, v11
	v_max_u32_e32 v11, v10, v11
	v_mov_b32_e32 v10, v22
	v_xor_b32_e32 v21, 32, v20
	v_lshlrev_b32_e32 v21, 2, v21
	ds_bpermute_b32 v12, v21, v4
	ds_bpermute_b32 v13, v21, v5
	ds_bpermute_b32 v14, v21, v6
	ds_bpermute_b32 v15, v21, v7
	ds_bpermute_b32 v16, v21, v8
	ds_bpermute_b32 v17, v21, v9
	ds_bpermute_b32 v18, v21, v10
	ds_bpermute_b32 v19, v21, v11
	v_bfe_u32 v22, v20, 5, 1
	v_cmp_eq_u32_e32 vcc, 0, v22
	s_waitcnt lgkmcnt(6)
	v_min_u32_e32 v22, v4, v12
	v_max_u32_e32 v23, v4, v12
	v_min_u32_e32 v24, v5, v13
	v_max_u32_e32 v25, v5, v13
	v_cndmask_b32_e32 v4, v23, v22, vcc
	v_cndmask_b32_e32 v5, v25, v24, vcc
	s_waitcnt lgkmcnt(4)
	v_min_u32_e32 v22, v6, v14
	v_max_u32_e32 v23, v6, v14
	v_min_u32_e32 v24, v7, v15
	v_max_u32_e32 v25, v7, v15
	v_cndmask_b32_e32 v6, v23, v22, vcc
	v_cndmask_b32_e32 v7, v25, v24, vcc
	s_waitcnt lgkmcnt(2)
	v_min_u32_e32 v22, v8, v16
	v_max_u32_e32 v23, v8, v16
	v_min_u32_e32 v24, v9, v17
	v_max_u32_e32 v25, v9, v17
	v_cndmask_b32_e32 v8, v23, v22, vcc
	v_cndmask_b32_e32 v9, v25, v24, vcc
	s_waitcnt lgkmcnt(0)
	v_min_u32_e32 v22, v10, v18
	v_max_u32_e32 v23, v10, v18
	v_min_u32_e32 v24, v11, v19
	v_max_u32_e32 v25, v11, v19
	v_cndmask_b32_e32 v10, v23, v22, vcc
	v_cndmask_b32_e32 v11, v25, v24, vcc
	v_xor_b32_e32 v21, 16, v20
	v_lshlrev_b32_e32 v21, 2, v21
	ds_bpermute_b32 v12, v21, v4
	ds_bpermute_b32 v13, v21, v5
	ds_bpermute_b32 v14, v21, v6
	ds_bpermute_b32 v15, v21, v7
	ds_bpermute_b32 v16, v21, v8
	ds_bpermute_b32 v17, v21, v9
	ds_bpermute_b32 v18, v21, v10
	ds_bpermute_b32 v19, v21, v11
	v_bfe_u32 v22, v20, 4, 1
	v_cmp_eq_u32_e32 vcc, 0, v22
	s_waitcnt lgkmcnt(6)
	v_min_u32_e32 v22, v4, v12
	v_max_u32_e32 v23, v4, v12
	v_min_u32_e32 v24, v5, v13
	v_max_u32_e32 v25, v5, v13
	v_cndmask_b32_e32 v4, v23, v22, vcc
	v_cndmask_b32_e32 v5, v25, v24, vcc
	s_waitcnt lgkmcnt(4)
	v_min_u32_e32 v22, v6, v14
	v_max_u32_e32 v23, v6, v14
	v_min_u32_e32 v24, v7, v15
	v_max_u32_e32 v25, v7, v15
	v_cndmask_b32_e32 v6, v23, v22, vcc
	v_cndmask_b32_e32 v7, v25, v24, vcc
	s_waitcnt lgkmcnt(2)
	v_min_u32_e32 v22, v8, v16
	v_max_u32_e32 v23, v8, v16
	v_min_u32_e32 v24, v9, v17
	v_max_u32_e32 v25, v9, v17
	v_cndmask_b32_e32 v8, v23, v22, vcc
	v_cndmask_b32_e32 v9, v25, v24, vcc
	s_waitcnt lgkmcnt(0)
	v_min_u32_e32 v22, v10, v18
	v_max_u32_e32 v23, v10, v18
	v_min_u32_e32 v24, v11, v19
	v_max_u32_e32 v25, v11, v19
	v_cndmask_b32_e32 v10, v23, v22, vcc
	v_cndmask_b32_e32 v11, v25, v24, vcc
	v_xor_b32_e32 v21, 8, v20
	v_lshlrev_b32_e32 v21, 2, v21
	ds_bpermute_b32 v12, v21, v4
	ds_bpermute_b32 v13, v21, v5
	ds_bpermute_b32 v14, v21, v6
	ds_bpermute_b32 v15, v21, v7
	ds_bpermute_b32 v16, v21, v8
	ds_bpermute_b32 v17, v21, v9
	ds_bpermute_b32 v18, v21, v10
	ds_bpermute_b32 v19, v21, v11
	v_bfe_u32 v22, v20, 3, 1
	v_cmp_eq_u32_e32 vcc, 0, v22
	s_waitcnt lgkmcnt(6)
	v_min_u32_e32 v22, v4, v12
	v_max_u32_e32 v23, v4, v12
	v_min_u32_e32 v24, v5, v13
	v_max_u32_e32 v25, v5, v13
	v_cndmask_b32_e32 v4, v23, v22, vcc
	v_cndmask_b32_e32 v5, v25, v24, vcc
	s_waitcnt lgkmcnt(4)
	v_min_u32_e32 v22, v6, v14
	v_max_u32_e32 v23, v6, v14
	v_min_u32_e32 v24, v7, v15
	v_max_u32_e32 v25, v7, v15
	v_cndmask_b32_e32 v6, v23, v22, vcc
	v_cndmask_b32_e32 v7, v25, v24, vcc
	s_waitcnt lgkmcnt(2)
	v_min_u32_e32 v22, v8, v16
	v_max_u32_e32 v23, v8, v16
	v_min_u32_e32 v24, v9, v17
	v_max_u32_e32 v25, v9, v17
	v_cndmask_b32_e32 v8, v23, v22, vcc
	v_cndmask_b32_e32 v9, v25, v24, vcc
	s_waitcnt lgkmcnt(0)
	v_min_u32_e32 v22, v10, v18
	v_max_u32_e32 v23, v10, v18
	v_min_u32_e32 v24, v11, v19
	v_max_u32_e32 v25, v11, v19
	v_cndmask_b32_e32 v10, v23, v22, vcc
	v_cndmask_b32_e32 v11, v25, v24, vcc
	v_and_b32_e32 v22, 0x7f, v4
	v_and_b32_e32 v23, 0x7f, v5
	v_lshl_add_u32 v22, v22, 4, v255
	v_lshl_add_u32 v23, v23, 4, v255
	ds_read_b128 v[28:31], v22 offset:0
	ds_read_b128 v[32:35], v23 offset:0
	v_and_b32_e32 v22, 0x7f, v6
	v_and_b32_e32 v23, 0x7f, v7
	v_lshl_add_u32 v22, v22, 4, v255
	v_lshl_add_u32 v23, v23, 4, v255
	ds_read_b128 v[36:39], v22 offset:2048
	ds_read_b128 v[40:43], v23 offset:2048
	v_and_b32_e32 v22, 0x7f, v8
	v_and_b32_e32 v23, 0x7f, v9
	v_lshl_add_u32 v22, v22, 4, v255
	v_lshl_add_u32 v23, v23, 4, v255
	ds_read_b128 v[44:47], v22 offset:4096
	ds_read_b128 v[48:51], v23 offset:4096
	v_and_b32_e32 v22, 0x7f, v10
	v_and_b32_e32 v23, 0x7f, v11
	v_lshl_add_u32 v22, v22, 4, v255
	v_lshl_add_u32 v23, v23, 4, v255
	ds_read_b128 v[52:55], v22 offset:6144
	ds_read_b128 v[56:59], v23 offset:6144
	v_lshl_add_u32 v21, v20, 4, v255
	s_waitcnt lgkmcnt(0)
	ds_write_b128 v21, v[28:31] offset:0
	ds_write_b128 v21, v[32:35] offset:1024
	ds_write_b128 v21, v[36:39] offset:2048
	ds_write_b128 v21, v[40:43] offset:3072
	ds_write_b128 v21, v[44:47] offset:4096
	ds_write_b128 v21, v[48:51] offset:5120
	ds_write_b128 v21, v[52:55] offset:6144
	ds_write_b128 v21, v[56:59] offset:7168
	s_waitcnt lgkmcnt(0)
	v_and_b32_e32 v8, 63, v214
	v_lshl_add_u32 v4, v8, 7, v255
	ds_read_b32 v5, v4
	ds_read_b32 v6, v4 offset:112
	s_waitcnt lgkmcnt(0)
	v_add_u32_e32 v5, v5, v6
	v_lshl_or_b32 v60, v5, 6, v8
	v_xor_b32_e32 v9, 1, v8
	v_lshlrev_b32_e32 v9, 2, v9
	ds_bpermute_b32 v5, v9, v60
	v_bfe_u32 v13, v8, 0, 1
	v_bfe_u32 v10, v8, 1, 1
	v_xor_b32_e32 v13, v13, v10
	v_cmp_eq_u32_e32 vcc, 0, v13
	s_waitcnt lgkmcnt(0)
	v_min_u32_e32 v10, v60, v5
	v_max_u32_e32 v12, v60, v5
	v_cndmask_b32_e32 v60, v12, v10, vcc
	v_xor_b32_e32 v9, 2, v8
	v_lshlrev_b32_e32 v9, 2, v9
	ds_bpermute_b32 v5, v9, v60
	v_bfe_u32 v13, v8, 1, 1
	v_bfe_u32 v10, v8, 2, 1
	v_xor_b32_e32 v13, v13, v10
	v_cmp_eq_u32_e32 vcc, 0, v13
	s_waitcnt lgkmcnt(0)
	v_min_u32_e32 v10, v60, v5
	v_max_u32_e32 v12, v60, v5
	v_cndmask_b32_e32 v60, v12, v10, vcc
	v_xor_b32_e32 v9, 1, v8
	v_lshlrev_b32_e32 v9, 2, v9
	ds_bpermute_b32 v5, v9, v60
	v_bfe_u32 v13, v8, 0, 1
	v_bfe_u32 v10, v8, 2, 1
	v_xor_b32_e32 v13, v13, v10
	v_cmp_eq_u32_e32 vcc, 0, v13
	s_waitcnt lgkmcnt(0)
	v_min_u32_e32 v10, v60, v5
	v_max_u32_e32 v12, v60, v5
	v_cndmask_b32_e32 v60, v12, v10, vcc
	v_xor_b32_e32 v9, 4, v8
	v_lshlrev_b32_e32 v9, 2, v9
	ds_bpermute_b32 v5, v9, v60
	v_bfe_u32 v13, v8, 2, 1
	v_bfe_u32 v10, v8, 3, 1
	v_xor_b32_e32 v13, v13, v10
	v_cmp_eq_u32_e32 vcc, 0, v13
	s_waitcnt lgkmcnt(0)
	v_min_u32_e32 v10, v60, v5
	v_max_u32_e32 v12, v60, v5
	v_cndmask_b32_e32 v60, v12, v10, vcc
	v_xor_b32_e32 v9, 2, v8
	v_lshlrev_b32_e32 v9, 2, v9
	ds_bpermute_b32 v5, v9, v60
	v_bfe_u32 v13, v8, 1, 1
	v_bfe_u32 v10, v8, 3, 1
	v_xor_b32_e32 v13, v13, v10
	v_cmp_eq_u32_e32 vcc, 0, v13
	s_waitcnt lgkmcnt(0)
	v_min_u32_e32 v10, v60, v5
	v_max_u32_e32 v12, v60, v5
	v_cndmask_b32_e32 v60, v12, v10, vcc
	v_xor_b32_e32 v9, 1, v8
	v_lshlrev_b32_e32 v9, 2, v9
	ds_bpermute_b32 v5, v9, v60
	v_bfe_u32 v13, v8, 0, 1
	v_bfe_u32 v10, v8, 3, 1
	v_xor_b32_e32 v13, v13, v10
	v_cmp_eq_u32_e32 vcc, 0, v13
	s_waitcnt lgkmcnt(0)
	v_min_u32_e32 v10, v60, v5
	v_max_u32_e32 v12, v60, v5
	v_cndmask_b32_e32 v60, v12, v10, vcc
	v_xor_b32_e32 v9, 8, v8
	v_lshlrev_b32_e32 v9, 2, v9
	ds_bpermute_b32 v5, v9, v60
	v_bfe_u32 v13, v8, 3, 1
	v_bfe_u32 v10, v8, 4, 1
	v_xor_b32_e32 v13, v13, v10
	v_cmp_eq_u32_e32 vcc, 0, v13
	s_waitcnt lgkmcnt(0)
	v_min_u32_e32 v10, v60, v5
	v_max_u32_e32 v12, v60, v5
	v_cndmask_b32_e32 v60, v12, v10, vcc
	v_xor_b32_e32 v9, 4, v8
	v_lshlrev_b32_e32 v9, 2, v9
	ds_bpermute_b32 v5, v9, v60
	v_bfe_u32 v13, v8, 2, 1
	v_bfe_u32 v10, v8, 4, 1
	v_xor_b32_e32 v13, v13, v10
	v_cmp_eq_u32_e32 vcc, 0, v13
	s_waitcnt lgkmcnt(0)
	v_min_u32_e32 v10, v60, v5
	v_max_u32_e32 v12, v60, v5
	v_cndmask_b32_e32 v60, v12, v10, vcc
	v_xor_b32_e32 v9, 2, v8
	v_lshlrev_b32_e32 v9, 2, v9
	ds_bpermute_b32 v5, v9, v60
	v_bfe_u32 v13, v8, 1, 1
	v_bfe_u32 v10, v8, 4, 1
	v_xor_b32_e32 v13, v13, v10
	v_cmp_eq_u32_e32 vcc, 0, v13
	s_waitcnt lgkmcnt(0)
	v_min_u32_e32 v10, v60, v5
	v_max_u32_e32 v12, v60, v5
	v_cndmask_b32_e32 v60, v12, v10, vcc
	v_xor_b32_e32 v9, 1, v8
	v_lshlrev_b32_e32 v9, 2, v9
	ds_bpermute_b32 v5, v9, v60
	v_bfe_u32 v13, v8, 0, 1
	v_bfe_u32 v10, v8, 4, 1
	v_xor_b32_e32 v13, v13, v10
	v_cmp_eq_u32_e32 vcc, 0, v13
	s_waitcnt lgkmcnt(0)
	v_min_u32_e32 v10, v60, v5
	v_max_u32_e32 v12, v60, v5
	v_cndmask_b32_e32 v60, v12, v10, vcc
	v_xor_b32_e32 v9, 16, v8
	v_lshlrev_b32_e32 v9, 2, v9
	ds_bpermute_b32 v5, v9, v60
	v_bfe_u32 v13, v8, 4, 1
	v_bfe_u32 v10, v8, 5, 1
	v_xor_b32_e32 v13, v13, v10
	v_cmp_eq_u32_e32 vcc, 0, v13
	s_waitcnt lgkmcnt(0)
	v_min_u32_e32 v10, v60, v5
	v_max_u32_e32 v12, v60, v5
	v_cndmask_b32_e32 v60, v12, v10, vcc
	v_xor_b32_e32 v9, 8, v8
	v_lshlrev_b32_e32 v9, 2, v9
	ds_bpermute_b32 v5, v9, v60
	v_bfe_u32 v13, v8, 3, 1
	v_bfe_u32 v10, v8, 5, 1
	v_xor_b32_e32 v13, v13, v10
	v_cmp_eq_u32_e32 vcc, 0, v13
	s_waitcnt lgkmcnt(0)
	v_min_u32_e32 v10, v60, v5
	v_max_u32_e32 v12, v60, v5
	v_cndmask_b32_e32 v60, v12, v10, vcc
	v_xor_b32_e32 v9, 4, v8
	v_lshlrev_b32_e32 v9, 2, v9
	ds_bpermute_b32 v5, v9, v60
	v_bfe_u32 v13, v8, 2, 1
	v_bfe_u32 v10, v8, 5, 1
	v_xor_b32_e32 v13, v13, v10
	v_cmp_eq_u32_e32 vcc, 0, v13
	s_waitcnt lgkmcnt(0)
	v_min_u32_e32 v10, v60, v5
	v_max_u32_e32 v12, v60, v5
	v_cndmask_b32_e32 v60, v12, v10, vcc
	v_xor_b32_e32 v9, 2, v8
	v_lshlrev_b32_e32 v9, 2, v9
	ds_bpermute_b32 v5, v9, v60
	v_bfe_u32 v13, v8, 1, 1
	v_bfe_u32 v10, v8, 5, 1
	v_xor_b32_e32 v13, v13, v10
	v_cmp_eq_u32_e32 vcc, 0, v13
	s_waitcnt lgkmcnt(0)
	v_min_u32_e32 v10, v60, v5
	v_max_u32_e32 v12, v60, v5
	v_cndmask_b32_e32 v60, v12, v10, vcc
	v_xor_b32_e32 v9, 1, v8
	v_lshlrev_b32_e32 v9, 2, v9
	ds_bpermute_b32 v5, v9, v60
	v_bfe_u32 v13, v8, 0, 1
	v_bfe_u32 v10, v8, 5, 1
	v_xor_b32_e32 v13, v13, v10
	v_cmp_eq_u32_e32 vcc, 0, v13
	s_waitcnt lgkmcnt(0)
	v_min_u32_e32 v10, v60, v5
	v_max_u32_e32 v12, v60, v5
	v_cndmask_b32_e32 v60, v12, v10, vcc
	v_xor_b32_e32 v9, 32, v8
	v_lshlrev_b32_e32 v9, 2, v9
	ds_bpermute_b32 v5, v9, v60
	v_bfe_u32 v13, v8, 5, 1
	v_cmp_eq_u32_e32 vcc, 0, v13
	s_waitcnt lgkmcnt(0)
	v_min_u32_e32 v10, v60, v5
	v_max_u32_e32 v12, v60, v5
	v_cndmask_b32_e32 v60, v12, v10, vcc
	v_xor_b32_e32 v9, 16, v8
	v_lshlrev_b32_e32 v9, 2, v9
	ds_bpermute_b32 v5, v9, v60
	v_bfe_u32 v13, v8, 4, 1
	v_cmp_eq_u32_e32 vcc, 0, v13
	s_waitcnt lgkmcnt(0)
	v_min_u32_e32 v10, v60, v5
	v_max_u32_e32 v12, v60, v5
	v_cndmask_b32_e32 v60, v12, v10, vcc
	v_xor_b32_e32 v9, 8, v8
	v_lshlrev_b32_e32 v9, 2, v9
	ds_bpermute_b32 v5, v9, v60
	v_bfe_u32 v13, v8, 3, 1
	v_cmp_eq_u32_e32 vcc, 0, v13
	s_waitcnt lgkmcnt(0)
	v_min_u32_e32 v10, v60, v5
	v_max_u32_e32 v12, v60, v5
	v_cndmask_b32_e32 v60, v12, v10, vcc
	v_xor_b32_e32 v9, 4, v8
	v_lshlrev_b32_e32 v9, 2, v9
	ds_bpermute_b32 v5, v9, v60
	v_bfe_u32 v13, v8, 2, 1
	v_cmp_eq_u32_e32 vcc, 0, v13
	s_waitcnt lgkmcnt(0)
	v_min_u32_e32 v10, v60, v5
	v_max_u32_e32 v12, v60, v5
	v_cndmask_b32_e32 v60, v12, v10, vcc
	v_xor_b32_e32 v9, 2, v8
	v_lshlrev_b32_e32 v9, 2, v9
	ds_bpermute_b32 v5, v9, v60
	v_bfe_u32 v13, v8, 1, 1
	v_cmp_eq_u32_e32 vcc, 0, v13
	s_waitcnt lgkmcnt(0)
	v_min_u32_e32 v10, v60, v5
	v_max_u32_e32 v12, v60, v5
	v_cndmask_b32_e32 v60, v12, v10, vcc
	v_xor_b32_e32 v9, 1, v8
	v_lshlrev_b32_e32 v9, 2, v9
	ds_bpermute_b32 v5, v9, v60
	v_bfe_u32 v13, v8, 0, 1
	v_cmp_eq_u32_e32 vcc, 0, v13
	s_waitcnt lgkmcnt(0)
	v_min_u32_e32 v10, v60, v5
	v_max_u32_e32 v12, v60, v5
	v_cndmask_b32_e32 v60, v12, v10, vcc
	s_waitcnt vmcnt(0)
	v_mov_b32_e32 v4, v216
	v_mov_b32_e32 v5, v217
	v_mov_b32_e32 v6, v218
	v_mov_b32_e32 v7, v219
	v_mov_b32_e32 v8, v220
	v_mov_b32_e32 v9, v221
	v_mov_b32_e32 v10, v222
	v_mov_b32_e32 v11, v223
	v_mov_b32_e32 v12, v224
	v_mov_b32_e32 v13, v225
	v_mov_b32_e32 v14, v226
	v_mov_b32_e32 v15, v227
	v_mov_b32_e32 v16, v228
	v_mov_b32_e32 v17, v229
	v_mov_b32_e32 v18, v230
	v_mov_b32_e32 v19, v231
	v_mov_b32_e32 v20, v232
	v_mov_b32_e32 v21, v233
	v_mov_b32_e32 v22, v234
	v_mov_b32_e32 v23, v235
	v_mov_b32_e32 v24, v236
	v_mov_b32_e32 v25, v237
	v_mov_b32_e32 v26, v238
	v_mov_b32_e32 v27, v239
	v_mov_b32_e32 v28, v240
	v_mov_b32_e32 v29, v241
	v_mov_b32_e32 v30, v242
	v_mov_b32_e32 v31, v243
	v_mov_b32_e32 v32, v244
	v_mov_b32_e32 v33, v245
	v_mov_b32_e32 v34, v246
	v_mov_b32_e32 v35, v247
	v_lshlrev_b32_e32 v96, 16, v4
	v_and_b32_e32 v97, 0xffff0000, v4
	v_lshlrev_b32_e32 v92, 16, v8
	v_and_b32_e32 v93, 0xffff0000, v8
	v_lshlrev_b32_e32 v98, 16, v5
	v_and_b32_e32 v99, 0xffff0000, v5
	v_lshlrev_b32_e32 v94, 16, v9
	v_and_b32_e32 v95, 0xffff0000, v9
	v_lshlrev_b32_e32 v100, 16, v6
	v_and_b32_e32 v101, 0xffff0000, v6
	v_lshlrev_b32_e32 v104, 16, v10
	v_and_b32_e32 v105, 0xffff0000, v10
	v_lshlrev_b32_e32 v102, 16, v7
	v_and_b32_e32 v103, 0xffff0000, v7
	v_lshlrev_b32_e32 v106, 16, v11
	v_and_b32_e32 v107, 0xffff0000, v11
	v_lshlrev_b32_e32 v134, 16, v12
	v_and_b32_e32 v135, 0xffff0000, v12
	v_lshlrev_b32_e32 v148, 16, v16
	v_and_b32_e32 v149, 0xffff0000, v16
	v_lshlrev_b32_e32 v142, 16, v13
	v_and_b32_e32 v143, 0xffff0000, v13
	v_lshlrev_b32_e32 v150, 16, v17
	v_and_b32_e32 v151, 0xffff0000, v17
	v_lshlrev_b32_e32 v144, 16, v14
	v_and_b32_e32 v145, 0xffff0000, v14
	v_lshlrev_b32_e32 v152, 16, v18
	v_and_b32_e32 v153, 0xffff0000, v18
	v_lshlrev_b32_e32 v146, 16, v15
	v_and_b32_e32 v147, 0xffff0000, v15
	v_lshlrev_b32_e32 v154, 16, v19
	v_and_b32_e32 v155, 0xffff0000, v19
	v_lshlrev_b32_e32 v216, 16, v20
	v_and_b32_e32 v217, 0xffff0000, v20
	v_lshlrev_b32_e32 v224, 16, v24
	v_and_b32_e32 v225, 0xffff0000, v24
	v_lshlrev_b32_e32 v218, 16, v21
	v_and_b32_e32 v219, 0xffff0000, v21
	v_lshlrev_b32_e32 v226, 16, v25
	v_and_b32_e32 v227, 0xffff0000, v25
	v_lshlrev_b32_e32 v220, 16, v22
	v_and_b32_e32 v221, 0xffff0000, v22
	v_lshlrev_b32_e32 v228, 16, v26
	v_and_b32_e32 v229, 0xffff0000, v26
	v_lshlrev_b32_e32 v222, 16, v23
	v_and_b32_e32 v223, 0xffff0000, v23
	v_lshlrev_b32_e32 v230, 16, v27
	v_and_b32_e32 v231, 0xffff0000, v27
	v_lshlrev_b32_e32 v232, 16, v28
	v_and_b32_e32 v233, 0xffff0000, v28
	v_lshlrev_b32_e32 v70, 16, v32
	v_and_b32_e32 v71, 0xffff0000, v32
	v_lshlrev_b32_e32 v234, 16, v29
	v_and_b32_e32 v235, 0xffff0000, v29
	v_lshlrev_b32_e32 v72, 16, v33
	v_and_b32_e32 v73, 0xffff0000, v33
	v_lshlrev_b32_e32 v236, 16, v30
	v_and_b32_e32 v237, 0xffff0000, v30
	v_lshlrev_b32_e32 v74, 16, v34
	v_and_b32_e32 v75, 0xffff0000, v34
	v_lshlrev_b32_e32 v238, 16, v31
	v_and_b32_e32 v239, 0xffff0000, v31
	v_lshlrev_b32_e32 v2, 16, v35
	v_and_b32_e32 v3, 0xffff0000, v35
	v_mov_b32_e32 v108, 0
	v_mov_b32_e32 v109, 0
	v_mov_b32_e32 v110, 0
	v_mov_b32_e32 v111, 0
	v_mov_b32_e32 v112, 0
	v_mov_b32_e32 v113, 0
	v_mov_b32_e32 v114, 0
	v_mov_b32_e32 v115, 0
	v_mov_b32_e32 v116, 0
	v_mov_b32_e32 v117, 0
	v_mov_b32_e32 v118, 0
	v_mov_b32_e32 v119, 0
	v_mov_b32_e32 v120, 0
	v_mov_b32_e32 v121, 0
	v_mov_b32_e32 v122, 0
	v_mov_b32_e32 v123, 0
	v_mov_b32_e32 v124, 0
	v_mov_b32_e32 v125, 0
	v_mov_b32_e32 v126, 0
	v_mov_b32_e32 v127, 0
	v_mov_b32_e32 v128, 0
	v_mov_b32_e32 v129, 0
	v_mov_b32_e32 v130, 0
	v_mov_b32_e32 v131, 0
	v_mov_b32_e32 v132, 0
	v_mov_b32_e32 v133, 0
	v_mov_b32_e32 v136, 0
	v_mov_b32_e32 v137, 0
	v_mov_b32_e32 v138, 0
	v_mov_b32_e32 v139, 0
	v_mov_b32_e32 v140, 0
	v_mov_b32_e32 v141, 0
	v_mov_b32_e32 v188, 0
	v_mov_b32_e32 v189, 0
	v_mov_b32_e32 v190, 0
	v_mov_b32_e32 v191, 0
	v_mov_b32_e32 v192, 0
	v_mov_b32_e32 v193, 0
	v_mov_b32_e32 v194, 0
	v_mov_b32_e32 v195, 0
	v_mov_b32_e32 v196, 0
	v_mov_b32_e32 v197, 0
	v_mov_b32_e32 v198, 0
	v_mov_b32_e32 v199, 0
	v_mov_b32_e32 v200, 0
	v_mov_b32_e32 v201, 0
	v_mov_b32_e32 v202, 0
	v_mov_b32_e32 v203, 0
	v_mov_b32_e32 v204, 0
	v_mov_b32_e32 v205, 0
	v_mov_b32_e32 v206, 0
	v_mov_b32_e32 v207, 0
	v_mov_b32_e32 v208, 0
	v_mov_b32_e32 v209, 0
	v_mov_b32_e32 v210, 0
	v_mov_b32_e32 v211, 0
	v_mov_b32_e32 v212, 0
	v_mov_b32_e32 v213, 0
	v_mov_b32_e32 v186, 0
	v_mov_b32_e32 v187, 0
	v_mov_b32_e32 v66, 0
	v_mov_b32_e32 v67, 0
	v_mov_b32_e32 v68, 0
	v_mov_b32_e32 v69, 0
	v_lshl_add_u32 v61, v215, 4, v255
	s_mov_b32 s4, 0
	v_readlane_b32 s14, v60, s4
	s_and_b32 s14, s14, 63
	v_lshl_add_u32 v0, s14, 7, v61
	ds_read_b128 v[56:59], v0
	s_waitcnt lgkmcnt(0)
	v_readlane_b32 s5, v56, 0
	s_lshl_b32 s52, s5, 10
	s_add_u32 s56, s98, s52
	s_addc_u32 s57, s99, 0
	global_load_dwordx4 v[4:7], v62, s[56:57]
	v_readlane_b32 s6, v56, 32
	s_lshl_b32 s52, s6, 10
	s_add_u32 s56, s98, s52
	s_addc_u32 s57, s99, 0
	global_load_dwordx4 v[8:11], v62, s[56:57]
	v_readlane_b32 s7, v56, 16
	s_lshl_b32 s52, s7, 10
	s_add_u32 s56, s98, s52
	s_addc_u32 s57, s99, 0
	global_load_dwordx4 v[12:15], v62, s[56:57]
	v_readlane_b32 s8, v56, 48
	s_lshl_b32 s52, s8, 10
	s_add_u32 s56, s98, s52
	s_addc_u32 s57, s99, 0
	global_load_dwordx4 v[16:19], v62, s[56:57]
	v_readlane_b32 s9, v56, 8
	s_lshl_b32 s52, s9, 10
	s_add_u32 s56, s98, s52
	s_addc_u32 s57, s99, 0
	global_load_dwordx4 v[20:23], v62, s[56:57]
	v_readlane_b32 s11, v56, 40
	s_lshl_b32 s52, s11, 10
	s_add_u32 s56, s98, s52
	s_addc_u32 s57, s99, 0
	global_load_dwordx4 v[24:27], v62, s[56:57]
	v_readlane_b32 s13, v56, 24
	s_lshl_b32 s52, s13, 10
	s_add_u32 s56, s98, s52
	s_addc_u32 s57, s99, 0
	global_load_dwordx4 v[28:31], v62, s[56:57]
	v_readlane_b32 s16, v56, 56
	s_lshl_b32 s52, s16, 10
	s_add_u32 s56, s98, s52
	s_addc_u32 s57, s99, 0
	global_load_dwordx4 v[32:35], v62, s[56:57]
	s_lshl_b32 s52, s5, 9
	s_add_u32 s58, s100, s52
	s_addc_u32 s59, s101, 0
	global_load_dwordx2 v[36:37], v63, s[58:59]
	s_lshl_b32 s52, s6, 9
	s_add_u32 s58, s100, s52
	s_addc_u32 s59, s101, 0
	global_load_dwordx2 v[38:39], v63, s[58:59]
	s_lshl_b32 s52, s7, 9
	s_add_u32 s58, s100, s52
	s_addc_u32 s59, s101, 0
	global_load_dwordx2 v[40:41], v63, s[58:59]
	s_lshl_b32 s52, s8, 9
	s_add_u32 s58, s100, s52
	s_addc_u32 s59, s101, 0
	global_load_dwordx2 v[42:43], v63, s[58:59]
	s_lshl_b32 s52, s9, 9
	s_add_u32 s58, s100, s52
	s_addc_u32 s59, s101, 0
	global_load_dwordx2 v[44:45], v63, s[58:59]
	s_lshl_b32 s52, s11, 9
	s_add_u32 s58, s100, s52
	s_addc_u32 s59, s101, 0
	global_load_dwordx2 v[46:47], v63, s[58:59]
	s_lshl_b32 s52, s13, 9
	s_add_u32 s58, s100, s52
	s_addc_u32 s59, s101, 0
	global_load_dwordx2 v[48:49], v63, s[58:59]
	s_lshl_b32 s52, s16, 9
	s_add_u32 s58, s100, s52
	s_addc_u32 s59, s101, 0
	global_load_dwordx2 v[50:51], v63, s[58:59]
	v_mov_b32_e32 v52, v56
	v_mov_b32_e32 v53, v57
	v_mov_b32_e32 v54, v58
	v_mov_b32_e32 v55, v59
	s_lshr_b32 s15, s14, 4

.Lex_d9:
	v_mov_b32_e32 v52, v56
	v_mov_b32_e32 v53, v57
	v_mov_b32_e32 v54, v58
	v_mov_b32_e32 v55, v59
	s_lshr_b32 s15, s14, 4
	s_add_i32 s4, s4, 1
	s_cmp_lt_u32 s4, 64
	s_cbranch_scc1 .Lex_grp
	s_waitcnt vmcnt(0)
	s_lshl_b32 s10, s12, 2
	v_add_u32_e32 v64, s10, v79
	v_ashrrev_i32_e32 v65, 31, v64
	v_lshl_add_u64 v[64:65], s[28:29], 0, v[64:65]
	v_lshlrev_b64 v[0:1], 11, v[64:65]
	v_lshl_add_u64 v[0:1], v[80:81], 0, v[0:1]
	v_mov_b32_e32 v156, v134
	v_mov_b32_e32 v157, v135
	v_mov_b32_e32 v158, v142
	v_mov_b32_e32 v159, v143
	v_mov_b32_e32 v160, v144
	v_mov_b32_e32 v161, v145
	v_mov_b32_e32 v162, v146
	v_mov_b32_e32 v163, v147
	v_mov_b32_e32 v164, v148
	v_mov_b32_e32 v165, v149
	v_mov_b32_e32 v166, v150
	v_mov_b32_e32 v167, v151
	v_mov_b32_e32 v168, v152
	v_mov_b32_e32 v169, v153
	v_mov_b32_e32 v170, v154
	v_mov_b32_e32 v171, v155
	v_mov_b32_e32 v44, v2
	v_mov_b32_e32 v45, v3
	v_mov_b32_e32 v134, v108
	v_mov_b32_e32 v135, v109
	v_mov_b32_e32 v150, v110
	v_mov_b32_e32 v151, v111
	v_mov_b32_e32 v148, v112
	v_mov_b32_e32 v149, v113
	v_mov_b32_e32 v146, v114
	v_mov_b32_e32 v147, v115
	v_mov_b32_e32 v144, v116
	v_mov_b32_e32 v145, v117
	v_mov_b32_e32 v142, v118
	v_mov_b32_e32 v143, v119
	v_mov_b32_e32 v152, v120
	v_mov_b32_e32 v153, v121
	v_mov_b32_e32 v154, v122
	v_mov_b32_e32 v155, v123
	v_lshlrev_b64 v[0:1], 10, v[64:65]
	global_load_dwordx4 v[4:7], v[88:89], off
	global_load_dwordx4 v[8:11], v[90:91], off
	v_pk_fma_f32 v[16:17], v[96:97], s[26:27], v[134:135] op_sel_hi:[1,0,1]
	v_pk_fma_f32 v[18:19], v[98:99], s[26:27], v[150:151] op_sel_hi:[1,0,1]
	v_add_f32_e32 v2, 0, v16
	v_add_f32_e32 v2, v17, v2
	v_add_f32_e32 v2, v18, v2
	v_add_f32_e32 v2, v19, v2
	v_pk_fma_f32 v[20:21], v[100:101], s[26:27], v[148:149] op_sel_hi:[1,0,1]
	v_pk_fma_f32 v[22:23], v[102:103], s[26:27], v[146:147] op_sel_hi:[1,0,1]
	v_add_f32_e32 v2, v20, v2
	v_add_f32_e32 v2, v21, v2
	v_add_f32_e32 v2, v22, v2
	v_add_f32_e32 v2, v23, v2
	v_pk_fma_f32 v[24:25], v[92:93], s[26:27], v[144:145] op_sel_hi:[1,0,1]
	v_pk_fma_f32 v[26:27], v[94:95], s[26:27], v[142:143] op_sel_hi:[1,0,1]
	v_add_f32_e32 v2, v24, v2
	v_add_f32_e32 v2, v25, v2
	v_add_f32_e32 v2, v26, v2
	v_pk_fma_f32 v[12:13], v[104:105], s[26:27], v[152:153] op_sel_hi:[1,0,1]
	v_add_f32_e32 v2, v27, v2
	v_add_f32_e32 v2, v12, v2
	v_pk_fma_f32 v[14:15], v[106:107], s[26:27], v[154:155] op_sel_hi:[1,0,1]
	v_add_f32_e32 v2, v13, v2
	v_add_f32_e32 v2, v14, v2
	v_add_f32_e32 v2, v15, v2
	v_mov_b32_e32 v28, 0
	v_lshl_add_u64 v[0:1], v[0:1], 2, v[86:87]
	v_add_f32_dpp v2, v2, v2 quad_perm:[1,0,3,2] row_mask:0xf bank_mask:0xf bound_ctrl:1
	s_nop 0
	s_nop 0
	v_add_f32_dpp v2, v2, v2 quad_perm:[2,3,0,1] row_mask:0xf bank_mask:0xf bound_ctrl:1
	s_nop 0
	s_nop 0
	v_add_f32_dpp v2, v2, v2 row_half_mirror row_mask:0xf bank_mask:0xf bound_ctrl:1
	s_nop 1
	v_add_f32_dpp v2, v2, v2 row_mirror row_mask:0xf bank_mask:0xf bound_ctrl:1
	s_nop 1
	v_mov_b32_dpp v28, v2 row_bcast:15 row_mask:0xa bank_mask:0xf
	v_add_f32_e32 v2, v2, v28
	v_mov_b32_e32 v28, 0
	s_nop 1
	v_mov_b32_dpp v28, v2 row_bcast:31 row_mask:0xc bank_mask:0xf
	v_add_f32_e32 v2, v2, v28
	s_nop 0
	v_readlane_b32 s34, v2, 63
	s_nop 1
	v_mul_f32_e32 v2, s34, v180
	v_pk_add_f32 v[16:17], v[16:17], v[2:3] op_sel_hi:[1,0] neg_lo:[0,1] neg_hi:[0,1]
	v_pk_add_f32 v[18:19], v[18:19], v[2:3] op_sel_hi:[1,0] neg_lo:[0,1] neg_hi:[0,1]
	v_pk_mul_f32 v[28:29], v[16:17], v[16:17]
	v_pk_mul_f32 v[30:31], v[18:19], v[18:19]
	v_pk_add_f32 v[20:21], v[20:21], v[2:3] op_sel_hi:[1,0] neg_lo:[0,1] neg_hi:[0,1]
	v_pk_add_f32 v[22:23], v[22:23], v[2:3] op_sel_hi:[1,0] neg_lo:[0,1] neg_hi:[0,1]
	v_pk_add_f32 v[24:25], v[24:25], v[2:3] op_sel_hi:[1,0] neg_lo:[0,1] neg_hi:[0,1]
	v_pk_add_f32 v[26:27], v[26:27], v[2:3] op_sel_hi:[1,0] neg_lo:[0,1] neg_hi:[0,1]
	v_pk_add_f32 v[12:13], v[12:13], v[2:3] op_sel_hi:[1,0] neg_lo:[0,1] neg_hi:[0,1]
	v_pk_add_f32 v[14:15], v[14:15], v[2:3] op_sel_hi:[1,0] neg_lo:[0,1] neg_hi:[0,1]
	v_add_f32_e32 v2, v28, v29
	v_add_f32_e32 v2, v30, v2
	v_pk_mul_f32 v[32:33], v[20:21], v[20:21]
	v_add_f32_e32 v2, v31, v2
	v_add_f32_e32 v2, v32, v2
	v_pk_mul_f32 v[34:35], v[22:23], v[22:23]
	v_add_f32_e32 v2, v33, v2
	v_add_f32_e32 v2, v34, v2
	v_pk_mul_f32 v[36:37], v[24:25], v[24:25]
	v_add_f32_e32 v2, v35, v2
	v_add_f32_e32 v2, v36, v2
	v_pk_mul_f32 v[38:39], v[26:27], v[26:27]
	v_add_f32_e32 v2, v37, v2
	v_add_f32_e32 v2, v38, v2
	v_pk_mul_f32 v[40:41], v[12:13], v[12:13]
	v_add_f32_e32 v2, v39, v2
	v_add_f32_e32 v2, v40, v2
	v_pk_mul_f32 v[42:43], v[14:15], v[14:15]
	v_add_f32_e32 v2, v41, v2
	v_add_f32_e32 v2, v42, v2
	v_add_f32_e32 v2, v43, v2
	v_mov_b32_e32 v28, 0
	s_nop 0
	v_add_f32_dpp v2, v2, v2 quad_perm:[1,0,3,2] row_mask:0xf bank_mask:0xf bound_ctrl:1
	s_nop 1
	v_add_f32_dpp v2, v2, v2 quad_perm:[2,3,0,1] row_mask:0xf bank_mask:0xf bound_ctrl:1
	s_nop 1
	v_add_f32_dpp v2, v2, v2 row_half_mirror row_mask:0xf bank_mask:0xf bound_ctrl:1
	s_nop 1
	v_add_f32_dpp v2, v2, v2 row_mirror row_mask:0xf bank_mask:0xf bound_ctrl:1
	s_nop 1
	v_mov_b32_dpp v28, v2 row_bcast:15 row_mask:0xa bank_mask:0xf
	v_add_f32_e32 v2, v2, v28
	v_mov_b32_e32 v28, 0
	s_nop 1
	v_mov_b32_dpp v28, v2 row_bcast:31 row_mask:0xc bank_mask:0xf
	v_add_f32_e32 v2, v2, v28
	s_nop 0
	v_readlane_b32 s34, v2, 63
	s_nop 1
	v_fma_f32 v2, s34, v180, v177
	v_mul_f32_e32 v28, 0x4b800000, v2
	v_cmp_gt_f32_e32 vcc, s49, v2
	s_nop 1
	v_cndmask_b32_e32 v2, v2, v28, vcc
	v_rsq_f32_e32 v2, v2
	s_nop 0
	v_mul_f32_e32 v28, 0x45800000, v2
	v_cndmask_b32_e32 v2, v2, v28, vcc
	v_pk_mul_f32 v[16:17], v[16:17], v[2:3] op_sel_hi:[1,0]
	v_pk_mul_f32 v[18:19], v[18:19], v[2:3] op_sel_hi:[1,0]
	s_waitcnt vmcnt(0)
	v_pk_fma_f32 v[4:5], v[4:5], v[16:17], v[8:9]
	v_pk_fma_f32 v[6:7], v[6:7], v[18:19], v[10:11]
	global_store_dwordx4 v[0:1], v[4:7], off
	global_load_dwordx4 v[4:7], v[88:89], off offset:16
	s_nop 0
	global_load_dwordx4 v[8:11], v[90:91], off offset:16
	v_pk_mul_f32 v[16:17], v[22:23], v[2:3] op_sel_hi:[1,0]
	v_pk_mul_f32 v[18:19], v[20:21], v[2:3] op_sel_hi:[1,0]
	v_pk_mul_f32 v[14:15], v[14:15], v[2:3] op_sel_hi:[1,0]
	v_pk_mul_f32 v[12:13], v[12:13], v[2:3] op_sel_hi:[1,0]
	s_waitcnt vmcnt(0)
	v_pk_fma_f32 v[4:5], v[4:5], v[18:19], v[8:9]
	v_pk_fma_f32 v[6:7], v[6:7], v[16:17], v[10:11]
	global_store_dwordx4 v[0:1], v[4:7], off offset:16
	global_load_dwordx4 v[4:7], v[88:89], off offset:32
	s_nop 0
	global_load_dwordx4 v[8:11], v[90:91], off offset:32
	v_pk_mul_f32 v[16:17], v[26:27], v[2:3] op_sel_hi:[1,0]
	v_pk_mul_f32 v[18:19], v[24:25], v[2:3] op_sel_hi:[1,0]
	s_waitcnt vmcnt(0)
	v_pk_fma_f32 v[6:7], v[6:7], v[16:17], v[10:11]
	v_pk_fma_f32 v[4:5], v[4:5], v[18:19], v[8:9]
	global_store_dwordx4 v[0:1], v[4:7], off offset:32
	global_load_dwordx4 v[4:7], v[88:89], off offset:48
	s_nop 0
	global_load_dwordx4 v[8:11], v[90:91], off offset:48
	s_waitcnt vmcnt(0)
	v_pk_fma_f32 v[4:5], v[12:13], v[4:5], v[8:9]
	v_pk_fma_f32 v[6:7], v[14:15], v[6:7], v[10:11]
	global_store_dwordx4 v[0:1], v[4:7], off offset:48
	s_lshl_b32 s10, s12, 2
	s_add_i32 s10, s10, 1
	v_add_u32_e32 v64, s10, v79
	v_ashrrev_i32_e32 v65, 31, v64
	v_lshl_add_u64 v[64:65], s[28:29], 0, v[64:65]
	v_lshlrev_b64 v[0:1], 11, v[64:65]
	v_lshl_add_u64 v[0:1], v[80:81], 0, v[0:1]
	v_mov_b32_e32 v96, v156
	v_mov_b32_e32 v97, v157
	v_mov_b32_e32 v98, v158
	v_mov_b32_e32 v99, v159
	v_mov_b32_e32 v100, v160
	v_mov_b32_e32 v101, v161
	v_mov_b32_e32 v102, v162
	v_mov_b32_e32 v103, v163
	v_mov_b32_e32 v92, v164
	v_mov_b32_e32 v93, v165
	v_mov_b32_e32 v94, v166
	v_mov_b32_e32 v95, v167
	v_mov_b32_e32 v104, v168
	v_mov_b32_e32 v105, v169
	v_mov_b32_e32 v106, v170
	v_mov_b32_e32 v107, v171
	v_mov_b32_e32 v134, v124
	v_mov_b32_e32 v135, v125
	v_mov_b32_e32 v150, v126
	v_mov_b32_e32 v151, v127
	v_mov_b32_e32 v148, v128
	v_mov_b32_e32 v149, v129
	v_mov_b32_e32 v146, v130
	v_mov_b32_e32 v147, v131
	v_mov_b32_e32 v144, v132
	v_mov_b32_e32 v145, v133
	v_mov_b32_e32 v142, v136
	v_mov_b32_e32 v143, v137
	v_mov_b32_e32 v152, v138
	v_mov_b32_e32 v153, v139
	v_mov_b32_e32 v154, v140
	v_mov_b32_e32 v155, v141
	v_lshlrev_b64 v[0:1], 10, v[64:65]
	global_load_dwordx4 v[4:7], v[88:89], off
	global_load_dwordx4 v[8:11], v[90:91], off
	v_pk_fma_f32 v[16:17], v[96:97], s[26:27], v[134:135] op_sel_hi:[1,0,1]
	v_pk_fma_f32 v[18:19], v[98:99], s[26:27], v[150:151] op_sel_hi:[1,0,1]
	v_add_f32_e32 v2, 0, v16
	v_add_f32_e32 v2, v17, v2
	v_add_f32_e32 v2, v18, v2
	v_add_f32_e32 v2, v19, v2
	v_pk_fma_f32 v[20:21], v[100:101], s[26:27], v[148:149] op_sel_hi:[1,0,1]
	v_pk_fma_f32 v[22:23], v[102:103], s[26:27], v[146:147] op_sel_hi:[1,0,1]
	v_add_f32_e32 v2, v20, v2
	v_add_f32_e32 v2, v21, v2
	v_add_f32_e32 v2, v22, v2
	v_add_f32_e32 v2, v23, v2
	v_pk_fma_f32 v[24:25], v[92:93], s[26:27], v[144:145] op_sel_hi:[1,0,1]
	v_pk_fma_f32 v[26:27], v[94:95], s[26:27], v[142:143] op_sel_hi:[1,0,1]
	v_add_f32_e32 v2, v24, v2
	v_add_f32_e32 v2, v25, v2
	v_add_f32_e32 v2, v26, v2
	v_pk_fma_f32 v[12:13], v[104:105], s[26:27], v[152:153] op_sel_hi:[1,0,1]
	v_add_f32_e32 v2, v27, v2
	v_add_f32_e32 v2, v12, v2
	v_pk_fma_f32 v[14:15], v[106:107], s[26:27], v[154:155] op_sel_hi:[1,0,1]
	v_add_f32_e32 v2, v13, v2
	v_add_f32_e32 v2, v14, v2
	v_add_f32_e32 v2, v15, v2
	v_mov_b32_e32 v28, 0
	v_lshl_add_u64 v[0:1], v[0:1], 2, v[86:87]
	v_add_f32_dpp v2, v2, v2 quad_perm:[1,0,3,2] row_mask:0xf bank_mask:0xf bound_ctrl:1
	s_nop 0
	s_nop 0
	v_add_f32_dpp v2, v2, v2 quad_perm:[2,3,0,1] row_mask:0xf bank_mask:0xf bound_ctrl:1
	s_nop 0
	s_nop 0
	v_add_f32_dpp v2, v2, v2 row_half_mirror row_mask:0xf bank_mask:0xf bound_ctrl:1
	s_nop 1
	v_add_f32_dpp v2, v2, v2 row_mirror row_mask:0xf bank_mask:0xf bound_ctrl:1
	s_nop 1
	v_mov_b32_dpp v28, v2 row_bcast:15 row_mask:0xa bank_mask:0xf
	v_add_f32_e32 v2, v2, v28
	v_mov_b32_e32 v28, 0
	s_nop 1
	v_mov_b32_dpp v28, v2 row_bcast:31 row_mask:0xc bank_mask:0xf
	v_add_f32_e32 v2, v2, v28
	s_nop 0
	v_readlane_b32 s34, v2, 63
	s_nop 1
	v_mul_f32_e32 v2, s34, v180
	v_pk_add_f32 v[16:17], v[16:17], v[2:3] op_sel_hi:[1,0] neg_lo:[0,1] neg_hi:[0,1]
	v_pk_add_f32 v[18:19], v[18:19], v[2:3] op_sel_hi:[1,0] neg_lo:[0,1] neg_hi:[0,1]
	v_pk_mul_f32 v[28:29], v[16:17], v[16:17]
	v_pk_mul_f32 v[30:31], v[18:19], v[18:19]
	v_pk_add_f32 v[20:21], v[20:21], v[2:3] op_sel_hi:[1,0] neg_lo:[0,1] neg_hi:[0,1]
	v_pk_add_f32 v[22:23], v[22:23], v[2:3] op_sel_hi:[1,0] neg_lo:[0,1] neg_hi:[0,1]
	v_pk_add_f32 v[24:25], v[24:25], v[2:3] op_sel_hi:[1,0] neg_lo:[0,1] neg_hi:[0,1]
	v_pk_add_f32 v[26:27], v[26:27], v[2:3] op_sel_hi:[1,0] neg_lo:[0,1] neg_hi:[0,1]
	v_pk_add_f32 v[12:13], v[12:13], v[2:3] op_sel_hi:[1,0] neg_lo:[0,1] neg_hi:[0,1]
	v_pk_add_f32 v[14:15], v[14:15], v[2:3] op_sel_hi:[1,0] neg_lo:[0,1] neg_hi:[0,1]
	v_add_f32_e32 v2, v28, v29
	v_add_f32_e32 v2, v30, v2
	v_pk_mul_f32 v[32:33], v[20:21], v[20:21]
	v_add_f32_e32 v2, v31, v2
	v_add_f32_e32 v2, v32, v2
	v_pk_mul_f32 v[34:35], v[22:23], v[22:23]
	v_add_f32_e32 v2, v33, v2
	v_add_f32_e32 v2, v34, v2
	v_pk_mul_f32 v[36:37], v[24:25], v[24:25]
	v_add_f32_e32 v2, v35, v2
	v_add_f32_e32 v2, v36, v2
	v_pk_mul_f32 v[38:39], v[26:27], v[26:27]
	v_add_f32_e32 v2, v37, v2
	v_add_f32_e32 v2, v38, v2
	v_pk_mul_f32 v[40:41], v[12:13], v[12:13]
	v_add_f32_e32 v2, v39, v2
	v_add_f32_e32 v2, v40, v2
	v_pk_mul_f32 v[42:43], v[14:15], v[14:15]
	v_add_f32_e32 v2, v41, v2
	v_add_f32_e32 v2, v42, v2
	v_add_f32_e32 v2, v43, v2
	v_mov_b32_e32 v28, 0
	s_nop 0
	v_add_f32_dpp v2, v2, v2 quad_perm:[1,0,3,2] row_mask:0xf bank_mask:0xf bound_ctrl:1
	s_nop 1
	v_add_f32_dpp v2, v2, v2 quad_perm:[2,3,0,1] row_mask:0xf bank_mask:0xf bound_ctrl:1
	s_nop 1
	v_add_f32_dpp v2, v2, v2 row_half_mirror row_mask:0xf bank_mask:0xf bound_ctrl:1
	s_nop 1
	v_add_f32_dpp v2, v2, v2 row_mirror row_mask:0xf bank_mask:0xf bound_ctrl:1
	s_nop 1
	v_mov_b32_dpp v28, v2 row_bcast:15 row_mask:0xa bank_mask:0xf
	v_add_f32_e32 v2, v2, v28
	v_mov_b32_e32 v28, 0
	s_nop 1
	v_mov_b32_dpp v28, v2 row_bcast:31 row_mask:0xc bank_mask:0xf
	v_add_f32_e32 v2, v2, v28
	s_nop 0
	v_readlane_b32 s34, v2, 63
	s_nop 1
	v_fma_f32 v2, s34, v180, v177
	v_mul_f32_e32 v28, 0x4b800000, v2
	v_cmp_gt_f32_e32 vcc, s49, v2
	s_nop 1
	v_cndmask_b32_e32 v2, v2, v28, vcc
	v_rsq_f32_e32 v2, v2
	s_nop 0
	v_mul_f32_e32 v28, 0x45800000, v2
	v_cndmask_b32_e32 v2, v2, v28, vcc
	v_pk_mul_f32 v[16:17], v[16:17], v[2:3] op_sel_hi:[1,0]
	v_pk_mul_f32 v[18:19], v[18:19], v[2:3] op_sel_hi:[1,0]
	s_waitcnt vmcnt(0)
	v_pk_fma_f32 v[4:5], v[4:5], v[16:17], v[8:9]
	v_pk_fma_f32 v[6:7], v[6:7], v[18:19], v[10:11]
	global_store_dwordx4 v[0:1], v[4:7], off
	global_load_dwordx4 v[4:7], v[88:89], off offset:16
	s_nop 0
	global_load_dwordx4 v[8:11], v[90:91], off offset:16
	v_pk_mul_f32 v[16:17], v[22:23], v[2:3] op_sel_hi:[1,0]
	v_pk_mul_f32 v[18:19], v[20:21], v[2:3] op_sel_hi:[1,0]
	v_pk_mul_f32 v[14:15], v[14:15], v[2:3] op_sel_hi:[1,0]
	v_pk_mul_f32 v[12:13], v[12:13], v[2:3] op_sel_hi:[1,0]
	s_waitcnt vmcnt(0)
	v_pk_fma_f32 v[4:5], v[4:5], v[18:19], v[8:9]
	v_pk_fma_f32 v[6:7], v[6:7], v[16:17], v[10:11]
	global_store_dwordx4 v[0:1], v[4:7], off offset:16
	global_load_dwordx4 v[4:7], v[88:89], off offset:32
	s_nop 0
	global_load_dwordx4 v[8:11], v[90:91], off offset:32
	v_pk_mul_f32 v[16:17], v[26:27], v[2:3] op_sel_hi:[1,0]
	v_pk_mul_f32 v[18:19], v[24:25], v[2:3] op_sel_hi:[1,0]
	s_waitcnt vmcnt(0)
	v_pk_fma_f32 v[6:7], v[6:7], v[16:17], v[10:11]
	v_pk_fma_f32 v[4:5], v[4:5], v[18:19], v[8:9]
	global_store_dwordx4 v[0:1], v[4:7], off offset:32
	global_load_dwordx4 v[4:7], v[88:89], off offset:48
	s_nop 0
	global_load_dwordx4 v[8:11], v[90:91], off offset:48
	s_waitcnt vmcnt(0)
	v_pk_fma_f32 v[4:5], v[12:13], v[4:5], v[8:9]
	v_pk_fma_f32 v[6:7], v[14:15], v[6:7], v[10:11]
	global_store_dwordx4 v[0:1], v[4:7], off offset:48
	s_lshl_b32 s10, s12, 2
	s_add_i32 s10, s10, 2
	v_add_u32_e32 v64, s10, v79
	v_ashrrev_i32_e32 v65, 31, v64
	v_lshl_add_u64 v[64:65], s[28:29], 0, v[64:65]
	v_lshlrev_b64 v[0:1], 11, v[64:65]
	v_lshl_add_u64 v[0:1], v[80:81], 0, v[0:1]
	v_mov_b32_e32 v96, v216
	v_mov_b32_e32 v97, v217
	v_mov_b32_e32 v98, v218
	v_mov_b32_e32 v99, v219
	v_mov_b32_e32 v100, v220
	v_mov_b32_e32 v101, v221
	v_mov_b32_e32 v102, v222
	v_mov_b32_e32 v103, v223
	v_mov_b32_e32 v92, v224
	v_mov_b32_e32 v93, v225
	v_mov_b32_e32 v94, v226
	v_mov_b32_e32 v95, v227
	v_mov_b32_e32 v104, v228
	v_mov_b32_e32 v105, v229
	v_mov_b32_e32 v106, v230
	v_mov_b32_e32 v107, v231
	v_mov_b32_e32 v134, v188
	v_mov_b32_e32 v135, v189
	v_mov_b32_e32 v150, v190
	v_mov_b32_e32 v151, v191
	v_mov_b32_e32 v148, v192
	v_mov_b32_e32 v149, v193
	v_mov_b32_e32 v146, v194
	v_mov_b32_e32 v147, v195
	v_mov_b32_e32 v144, v196
	v_mov_b32_e32 v145, v197
	v_mov_b32_e32 v142, v198
	v_mov_b32_e32 v143, v199
	v_mov_b32_e32 v152, v200
	v_mov_b32_e32 v153, v201
	v_mov_b32_e32 v154, v202
	v_mov_b32_e32 v155, v203
	v_lshlrev_b64 v[0:1], 10, v[64:65]
	global_load_dwordx4 v[4:7], v[88:89], off
	global_load_dwordx4 v[8:11], v[90:91], off
	v_pk_fma_f32 v[16:17], v[96:97], s[26:27], v[134:135] op_sel_hi:[1,0,1]
	v_pk_fma_f32 v[18:19], v[98:99], s[26:27], v[150:151] op_sel_hi:[1,0,1]
	v_add_f32_e32 v2, 0, v16
	v_add_f32_e32 v2, v17, v2
	v_add_f32_e32 v2, v18, v2
	v_add_f32_e32 v2, v19, v2
	v_pk_fma_f32 v[20:21], v[100:101], s[26:27], v[148:149] op_sel_hi:[1,0,1]
	v_pk_fma_f32 v[22:23], v[102:103], s[26:27], v[146:147] op_sel_hi:[1,0,1]
	v_add_f32_e32 v2, v20, v2
	v_add_f32_e32 v2, v21, v2
	v_add_f32_e32 v2, v22, v2
	v_add_f32_e32 v2, v23, v2
	v_pk_fma_f32 v[24:25], v[92:93], s[26:27], v[144:145] op_sel_hi:[1,0,1]
	v_pk_fma_f32 v[26:27], v[94:95], s[26:27], v[142:143] op_sel_hi:[1,0,1]
	v_add_f32_e32 v2, v24, v2
	v_add_f32_e32 v2, v25, v2
	v_add_f32_e32 v2, v26, v2
	v_pk_fma_f32 v[12:13], v[104:105], s[26:27], v[152:153] op_sel_hi:[1,0,1]
	v_add_f32_e32 v2, v27, v2
	v_add_f32_e32 v2, v12, v2
	v_pk_fma_f32 v[14:15], v[106:107], s[26:27], v[154:155] op_sel_hi:[1,0,1]
	v_add_f32_e32 v2, v13, v2
	v_add_f32_e32 v2, v14, v2
	v_add_f32_e32 v2, v15, v2
	v_mov_b32_e32 v28, 0
	v_lshl_add_u64 v[0:1], v[0:1], 2, v[86:87]
	v_add_f32_dpp v2, v2, v2 quad_perm:[1,0,3,2] row_mask:0xf bank_mask:0xf bound_ctrl:1
	s_nop 0
	s_nop 0
	v_add_f32_dpp v2, v2, v2 quad_perm:[2,3,0,1] row_mask:0xf bank_mask:0xf bound_ctrl:1
	s_nop 0
	s_nop 0
	v_add_f32_dpp v2, v2, v2 row_half_mirror row_mask:0xf bank_mask:0xf bound_ctrl:1
	s_nop 1
	v_add_f32_dpp v2, v2, v2 row_mirror row_mask:0xf bank_mask:0xf bound_ctrl:1
	s_nop 1
	v_mov_b32_dpp v28, v2 row_bcast:15 row_mask:0xa bank_mask:0xf
	v_add_f32_e32 v2, v2, v28
	v_mov_b32_e32 v28, 0
	s_nop 1
	v_mov_b32_dpp v28, v2 row_bcast:31 row_mask:0xc bank_mask:0xf
	v_add_f32_e32 v2, v2, v28
	s_nop 0
	v_readlane_b32 s34, v2, 63
	s_nop 1
	v_mul_f32_e32 v2, s34, v180
	v_pk_add_f32 v[16:17], v[16:17], v[2:3] op_sel_hi:[1,0] neg_lo:[0,1] neg_hi:[0,1]
	v_pk_add_f32 v[18:19], v[18:19], v[2:3] op_sel_hi:[1,0] neg_lo:[0,1] neg_hi:[0,1]
	v_pk_mul_f32 v[28:29], v[16:17], v[16:17]
	v_pk_mul_f32 v[30:31], v[18:19], v[18:19]
	v_pk_add_f32 v[20:21], v[20:21], v[2:3] op_sel_hi:[1,0] neg_lo:[0,1] neg_hi:[0,1]
	v_pk_add_f32 v[22:23], v[22:23], v[2:3] op_sel_hi:[1,0] neg_lo:[0,1] neg_hi:[0,1]
	v_pk_add_f32 v[24:25], v[24:25], v[2:3] op_sel_hi:[1,0] neg_lo:[0,1] neg_hi:[0,1]
	v_pk_add_f32 v[26:27], v[26:27], v[2:3] op_sel_hi:[1,0] neg_lo:[0,1] neg_hi:[0,1]
	v_pk_add_f32 v[12:13], v[12:13], v[2:3] op_sel_hi:[1,0] neg_lo:[0,1] neg_hi:[0,1]
	v_pk_add_f32 v[14:15], v[14:15], v[2:3] op_sel_hi:[1,0] neg_lo:[0,1] neg_hi:[0,1]
	v_add_f32_e32 v2, v28, v29
	v_add_f32_e32 v2, v30, v2
	v_pk_mul_f32 v[32:33], v[20:21], v[20:21]
	v_add_f32_e32 v2, v31, v2
	v_add_f32_e32 v2, v32, v2
	v_pk_mul_f32 v[34:35], v[22:23], v[22:23]
	v_add_f32_e32 v2, v33, v2
	v_add_f32_e32 v2, v34, v2
	v_pk_mul_f32 v[36:37], v[24:25], v[24:25]
	v_add_f32_e32 v2, v35, v2
	v_add_f32_e32 v2, v36, v2
	v_pk_mul_f32 v[38:39], v[26:27], v[26:27]
	v_add_f32_e32 v2, v37, v2
	v_add_f32_e32 v2, v38, v2
	v_pk_mul_f32 v[40:41], v[12:13], v[12:13]
	v_add_f32_e32 v2, v39, v2
	v_add_f32_e32 v2, v40, v2
	v_pk_mul_f32 v[42:43], v[14:15], v[14:15]
	v_add_f32_e32 v2, v41, v2
	v_add_f32_e32 v2, v42, v2
	v_add_f32_e32 v2, v43, v2
	v_mov_b32_e32 v28, 0
	s_nop 0
	v_add_f32_dpp v2, v2, v2 quad_perm:[1,0,3,2] row_mask:0xf bank_mask:0xf bound_ctrl:1
	s_nop 1
	v_add_f32_dpp v2, v2, v2 quad_perm:[2,3,0,1] row_mask:0xf bank_mask:0xf bound_ctrl:1
	s_nop 1
	v_add_f32_dpp v2, v2, v2 row_half_mirror row_mask:0xf bank_mask:0xf bound_ctrl:1
	s_nop 1
	v_add_f32_dpp v2, v2, v2 row_mirror row_mask:0xf bank_mask:0xf bound_ctrl:1
	s_nop 1
	v_mov_b32_dpp v28, v2 row_bcast:15 row_mask:0xa bank_mask:0xf
	v_add_f32_e32 v2, v2, v28
	v_mov_b32_e32 v28, 0
	s_nop 1
	v_mov_b32_dpp v28, v2 row_bcast:31 row_mask:0xc bank_mask:0xf
	v_add_f32_e32 v2, v2, v28
	s_nop 0
	v_readlane_b32 s34, v2, 63
	s_nop 1
	v_fma_f32 v2, s34, v180, v177
	v_mul_f32_e32 v28, 0x4b800000, v2
	v_cmp_gt_f32_e32 vcc, s49, v2
	s_nop 1
	v_cndmask_b32_e32 v2, v2, v28, vcc
	v_rsq_f32_e32 v2, v2
	s_nop 0
	v_mul_f32_e32 v28, 0x45800000, v2
	v_cndmask_b32_e32 v2, v2, v28, vcc
	v_pk_mul_f32 v[16:17], v[16:17], v[2:3] op_sel_hi:[1,0]
	v_pk_mul_f32 v[18:19], v[18:19], v[2:3] op_sel_hi:[1,0]
	s_waitcnt vmcnt(0)
	v_pk_fma_f32 v[4:5], v[4:5], v[16:17], v[8:9]
	v_pk_fma_f32 v[6:7], v[6:7], v[18:19], v[10:11]
	global_store_dwordx4 v[0:1], v[4:7], off
	global_load_dwordx4 v[4:7], v[88:89], off offset:16
	s_nop 0
	global_load_dwordx4 v[8:11], v[90:91], off offset:16
	v_pk_mul_f32 v[16:17], v[22:23], v[2:3] op_sel_hi:[1,0]
	v_pk_mul_f32 v[18:19], v[20:21], v[2:3] op_sel_hi:[1,0]
	v_pk_mul_f32 v[14:15], v[14:15], v[2:3] op_sel_hi:[1,0]
	v_pk_mul_f32 v[12:13], v[12:13], v[2:3] op_sel_hi:[1,0]
	s_waitcnt vmcnt(0)
	v_pk_fma_f32 v[4:5], v[4:5], v[18:19], v[8:9]
	v_pk_fma_f32 v[6:7], v[6:7], v[16:17], v[10:11]
	global_store_dwordx4 v[0:1], v[4:7], off offset:16
	global_load_dwordx4 v[4:7], v[88:89], off offset:32
	s_nop 0
	global_load_dwordx4 v[8:11], v[90:91], off offset:32
	v_pk_mul_f32 v[16:17], v[26:27], v[2:3] op_sel_hi:[1,0]
	v_pk_mul_f32 v[18:19], v[24:25], v[2:3] op_sel_hi:[1,0]
	s_waitcnt vmcnt(0)
	v_pk_fma_f32 v[6:7], v[6:7], v[16:17], v[10:11]
	v_pk_fma_f32 v[4:5], v[4:5], v[18:19], v[8:9]
	global_store_dwordx4 v[0:1], v[4:7], off offset:32
	global_load_dwordx4 v[4:7], v[88:89], off offset:48
	s_nop 0
	global_load_dwordx4 v[8:11], v[90:91], off offset:48
	s_waitcnt vmcnt(0)
	v_pk_fma_f32 v[4:5], v[12:13], v[4:5], v[8:9]
	v_pk_fma_f32 v[6:7], v[14:15], v[6:7], v[10:11]
	global_store_dwordx4 v[0:1], v[4:7], off offset:48
	s_lshl_b32 s10, s12, 2
	s_add_i32 s10, s10, 3
	v_add_u32_e32 v64, s10, v79
	v_ashrrev_i32_e32 v65, 31, v64
	v_lshl_add_u64 v[64:65], s[28:29], 0, v[64:65]
	v_lshlrev_b64 v[0:1], 11, v[64:65]
	v_lshl_add_u64 v[0:1], v[80:81], 0, v[0:1]
	v_mov_b32_e32 v96, v232
	v_mov_b32_e32 v97, v233
	v_mov_b32_e32 v98, v234
	v_mov_b32_e32 v99, v235
	v_mov_b32_e32 v100, v236
	v_mov_b32_e32 v101, v237
	v_mov_b32_e32 v102, v238
	v_mov_b32_e32 v103, v239
	v_mov_b32_e32 v92, v70
	v_mov_b32_e32 v93, v71
	v_mov_b32_e32 v94, v72
	v_mov_b32_e32 v95, v73
	v_mov_b32_e32 v104, v74
	v_mov_b32_e32 v105, v75
	v_mov_b32_e32 v106, v44
	v_mov_b32_e32 v107, v45
	v_mov_b32_e32 v134, v204
	v_mov_b32_e32 v135, v205
	v_mov_b32_e32 v150, v206
	v_mov_b32_e32 v151, v207
	v_mov_b32_e32 v148, v208
	v_mov_b32_e32 v149, v209
	v_mov_b32_e32 v146, v210
	v_mov_b32_e32 v147, v211
	v_mov_b32_e32 v144, v212
	v_mov_b32_e32 v145, v213
	v_mov_b32_e32 v142, v186
	v_mov_b32_e32 v143, v187
	v_mov_b32_e32 v152, v66
	v_mov_b32_e32 v153, v67
	v_mov_b32_e32 v154, v68
	v_mov_b32_e32 v155, v69
	v_lshlrev_b64 v[0:1], 10, v[64:65]
	global_load_dwordx4 v[4:7], v[88:89], off
	global_load_dwordx4 v[8:11], v[90:91], off
	v_pk_fma_f32 v[16:17], v[96:97], s[26:27], v[134:135] op_sel_hi:[1,0,1]
	v_pk_fma_f32 v[18:19], v[98:99], s[26:27], v[150:151] op_sel_hi:[1,0,1]
	v_add_f32_e32 v2, 0, v16
	v_add_f32_e32 v2, v17, v2
	v_add_f32_e32 v2, v18, v2
	v_add_f32_e32 v2, v19, v2
	v_pk_fma_f32 v[20:21], v[100:101], s[26:27], v[148:149] op_sel_hi:[1,0,1]
	v_pk_fma_f32 v[22:23], v[102:103], s[26:27], v[146:147] op_sel_hi:[1,0,1]
	v_add_f32_e32 v2, v20, v2
	v_add_f32_e32 v2, v21, v2
	v_add_f32_e32 v2, v22, v2
	v_add_f32_e32 v2, v23, v2
	v_pk_fma_f32 v[24:25], v[92:93], s[26:27], v[144:145] op_sel_hi:[1,0,1]
	v_pk_fma_f32 v[26:27], v[94:95], s[26:27], v[142:143] op_sel_hi:[1,0,1]
	v_add_f32_e32 v2, v24, v2
	v_add_f32_e32 v2, v25, v2
	v_add_f32_e32 v2, v26, v2
	v_pk_fma_f32 v[12:13], v[104:105], s[26:27], v[152:153] op_sel_hi:[1,0,1]
	v_add_f32_e32 v2, v27, v2
	v_add_f32_e32 v2, v12, v2
	v_pk_fma_f32 v[14:15], v[106:107], s[26:27], v[154:155] op_sel_hi:[1,0,1]
	v_add_f32_e32 v2, v13, v2
	v_add_f32_e32 v2, v14, v2
	v_add_f32_e32 v2, v15, v2
	v_mov_b32_e32 v28, 0
	v_lshl_add_u64 v[0:1], v[0:1], 2, v[86:87]
	v_add_f32_dpp v2, v2, v2 quad_perm:[1,0,3,2] row_mask:0xf bank_mask:0xf bound_ctrl:1
	s_nop 0
	s_nop 0
	v_add_f32_dpp v2, v2, v2 quad_perm:[2,3,0,1] row_mask:0xf bank_mask:0xf bound_ctrl:1
	s_nop 0
	s_nop 0
	v_add_f32_dpp v2, v2, v2 row_half_mirror row_mask:0xf bank_mask:0xf bound_ctrl:1
	s_nop 1
	v_add_f32_dpp v2, v2, v2 row_mirror row_mask:0xf bank_mask:0xf bound_ctrl:1
	s_nop 1
	v_mov_b32_dpp v28, v2 row_bcast:15 row_mask:0xa bank_mask:0xf
	v_add_f32_e32 v2, v2, v28
	v_mov_b32_e32 v28, 0
	s_nop 1
	v_mov_b32_dpp v28, v2 row_bcast:31 row_mask:0xc bank_mask:0xf
	v_add_f32_e32 v2, v2, v28
	s_nop 0
	v_readlane_b32 s34, v2, 63
	s_nop 1
	v_mul_f32_e32 v2, s34, v180
	v_pk_add_f32 v[16:17], v[16:17], v[2:3] op_sel_hi:[1,0] neg_lo:[0,1] neg_hi:[0,1]
	v_pk_add_f32 v[18:19], v[18:19], v[2:3] op_sel_hi:[1,0] neg_lo:[0,1] neg_hi:[0,1]
	v_pk_mul_f32 v[28:29], v[16:17], v[16:17]
	v_pk_mul_f32 v[30:31], v[18:19], v[18:19]
	v_pk_add_f32 v[20:21], v[20:21], v[2:3] op_sel_hi:[1,0] neg_lo:[0,1] neg_hi:[0,1]
	v_pk_add_f32 v[22:23], v[22:23], v[2:3] op_sel_hi:[1,0] neg_lo:[0,1] neg_hi:[0,1]
	v_pk_add_f32 v[24:25], v[24:25], v[2:3] op_sel_hi:[1,0] neg_lo:[0,1] neg_hi:[0,1]
	v_pk_add_f32 v[26:27], v[26:27], v[2:3] op_sel_hi:[1,0] neg_lo:[0,1] neg_hi:[0,1]
	v_pk_add_f32 v[12:13], v[12:13], v[2:3] op_sel_hi:[1,0] neg_lo:[0,1] neg_hi:[0,1]
	v_pk_add_f32 v[14:15], v[14:15], v[2:3] op_sel_hi:[1,0] neg_lo:[0,1] neg_hi:[0,1]
	v_add_f32_e32 v2, v28, v29
	v_add_f32_e32 v2, v30, v2
	v_pk_mul_f32 v[32:33], v[20:21], v[20:21]
	v_add_f32_e32 v2, v31, v2
	v_add_f32_e32 v2, v32, v2
	v_pk_mul_f32 v[34:35], v[22:23], v[22:23]
	v_add_f32_e32 v2, v33, v2
	v_add_f32_e32 v2, v34, v2
	v_pk_mul_f32 v[36:37], v[24:25], v[24:25]
	v_add_f32_e32 v2, v35, v2
	v_add_f32_e32 v2, v36, v2
	v_pk_mul_f32 v[38:39], v[26:27], v[26:27]
	v_add_f32_e32 v2, v37, v2
	v_add_f32_e32 v2, v38, v2
	v_pk_mul_f32 v[40:41], v[12:13], v[12:13]
	v_add_f32_e32 v2, v39, v2
	v_add_f32_e32 v2, v40, v2
	v_pk_mul_f32 v[42:43], v[14:15], v[14:15]
	v_add_f32_e32 v2, v41, v2
	v_add_f32_e32 v2, v42, v2
	v_add_f32_e32 v2, v43, v2
	v_mov_b32_e32 v28, 0
	s_nop 0
	v_add_f32_dpp v2, v2, v2 quad_perm:[1,0,3,2] row_mask:0xf bank_mask:0xf bound_ctrl:1
	s_nop 1
	v_add_f32_dpp v2, v2, v2 quad_perm:[2,3,0,1] row_mask:0xf bank_mask:0xf bound_ctrl:1
	s_nop 1
	v_add_f32_dpp v2, v2, v2 row_half_mirror row_mask:0xf bank_mask:0xf bound_ctrl:1
	s_nop 1
	v_add_f32_dpp v2, v2, v2 row_mirror row_mask:0xf bank_mask:0xf bound_ctrl:1
	s_nop 1
	v_mov_b32_dpp v28, v2 row_bcast:15 row_mask:0xa bank_mask:0xf
	v_add_f32_e32 v2, v2, v28
	v_mov_b32_e32 v28, 0
	s_nop 1
	v_mov_b32_dpp v28, v2 row_bcast:31 row_mask:0xc bank_mask:0xf
	v_add_f32_e32 v2, v2, v28
	s_nop 0
	v_readlane_b32 s34, v2, 63
	s_nop 1
	v_fma_f32 v2, s34, v180, v177
	v_mul_f32_e32 v28, 0x4b800000, v2
	v_cmp_gt_f32_e32 vcc, s49, v2
	s_nop 1
	v_cndmask_b32_e32 v2, v2, v28, vcc
	v_rsq_f32_e32 v2, v2
	s_nop 0
	v_mul_f32_e32 v28, 0x45800000, v2
	v_cndmask_b32_e32 v2, v2, v28, vcc
	v_pk_mul_f32 v[16:17], v[16:17], v[2:3] op_sel_hi:[1,0]
	v_pk_mul_f32 v[18:19], v[18:19], v[2:3] op_sel_hi:[1,0]
	s_waitcnt vmcnt(0)
	v_pk_fma_f32 v[4:5], v[4:5], v[16:17], v[8:9]
	v_pk_fma_f32 v[6:7], v[6:7], v[18:19], v[10:11]
	global_store_dwordx4 v[0:1], v[4:7], off
	global_load_dwordx4 v[4:7], v[88:89], off offset:16
	s_nop 0
	global_load_dwordx4 v[8:11], v[90:91], off offset:16
	v_pk_mul_f32 v[16:17], v[22:23], v[2:3] op_sel_hi:[1,0]
	v_pk_mul_f32 v[18:19], v[20:21], v[2:3] op_sel_hi:[1,0]
	v_pk_mul_f32 v[14:15], v[14:15], v[2:3] op_sel_hi:[1,0]
	v_pk_mul_f32 v[12:13], v[12:13], v[2:3] op_sel_hi:[1,0]
	s_waitcnt vmcnt(0)
	v_pk_fma_f32 v[4:5], v[4:5], v[18:19], v[8:9]
	v_pk_fma_f32 v[6:7], v[6:7], v[16:17], v[10:11]
	global_store_dwordx4 v[0:1], v[4:7], off offset:16
	global_load_dwordx4 v[4:7], v[88:89], off offset:32
	s_nop 0
	global_load_dwordx4 v[8:11], v[90:91], off offset:32
	v_pk_mul_f32 v[16:17], v[26:27], v[2:3] op_sel_hi:[1,0]
	v_pk_mul_f32 v[18:19], v[24:25], v[2:3] op_sel_hi:[1,0]
	s_waitcnt vmcnt(0)
	v_pk_fma_f32 v[6:7], v[6:7], v[16:17], v[10:11]
	v_pk_fma_f32 v[4:5], v[4:5], v[18:19], v[8:9]
	global_store_dwordx4 v[0:1], v[4:7], off offset:32
	global_load_dwordx4 v[4:7], v[88:89], off offset:48
	s_nop 0
	global_load_dwordx4 v[8:11], v[90:91], off offset:48
	s_waitcnt vmcnt(0)
	v_pk_fma_f32 v[4:5], v[12:13], v[4:5], v[8:9]
	v_pk_fma_f32 v[6:7], v[14:15], v[6:7], v[10:11]
	global_store_dwordx4 v[0:1], v[4:7], off offset:48
	s_add_i32 s12, s12, 1
	s_cmp_lt_u32 s12, 2
	s_cbranch_scc1 .Lex_half
	v_mov_b32_e32 v3, 0
	s_branch .LBB0_685
